# K-loop MFMA order: the two K-slice MFMAs of each accumulator issued back to back (accumulate pairs), on top of SGPR-base LDS-DMA addressing
# speedup vs baseline: 1.0092x; 1.0022x over previous
; #define PG8_STAGE(bufoff, gbase, voff) do { _Pragma("unroll") for (int _i = 0; _i < 2; ++_i) \
;         __builtin_amdgcn_global_load_lds((const unsigned*)((const char*)(gbase) + (voff)[_i]), (PG8_LAS unsigned*)(lds + (bufoff) + ldsw + _i * 8192), 16, 0, 0); } while (0)
; #define PG8_LDA(dst, b, h) do { _Pragma("unroll") for (int m = 0; m < 4; ++m) _Pragma("unroll") for (int k = 0; k < 2; ++k) dst[m][k] = *(const PG8_LAS bf16x8*)(lds + PG8_SA(b, h) + aoff + m * 2048 + k * 1024); } while (0)
; #define PG8_LDB(dst, b, h) do { _Pragma("unroll") for (int n = 0; n < 2; ++n) _Pragma("unroll") for (int k = 0; k < 2; ++k) dst[n][k] = *(const PG8_LAS bf16x8*)(lds + PG8_SB(b, h) + boff + n * 2048 + k * 1024); } while (0)
; #define PG8_MMA(ai, bj, At, Bt) do { __builtin_amdgcn_s_setprio(1); _Pragma("unroll") for (int m = 0; m < 4; ++m) _Pragma("unroll") for (int n = 0; n < 2; ++n) _Pragma("unroll") for (int k = 0; k < 2; ++k) \
;         acc[ai][bj][m][n] = __builtin_amdgcn_mfma_f32_16x16x32_bf16(Bt[n][k], At[m][k], acc[ai][bj][m][n], 0, 0, 0); __builtin_amdgcn_s_setprio(0); } while (0)
; template <class Epi, class Sched, bool ALIGN_EPI = false, bool SP2 = false>
; __device__ __forceinline__ void gemm_phase(PG8_LAS unsigned char* lds, const Gemm g, const Sched& S, const Epi& E) {
;     ...
;         for (int t = 0; t < ntc; t += 2) {
;             if constexpr (Epi::MID) { if (ntc == nt && t == (nt >> 1)) E.mid(acc, cur, wr, wc, fr, fq); }
;             const bool last = (t == ntc - 2);
;             const char* a1 = cA + (size_t)(t + 1) * kstep;
;             const char* a2 = last ? nA : cA + (size_t)(t + 2) * kstep; const char* b2 = last ? nB : cB + (size_t)(t + 2) * kstep;
;             const char* a3 = a2 + kstep; const char* b3 = b2 + kstep;
;             if (last && has_next) S.a_ready(nxt);
;             if constexpr (SP2) {
;             PG8_LDB(B0, 0, 0); PG8_LDB(B1, 0, 1); PG8_SCHED; PG8_LDA(At, 0, 0); PG8_STAGE(PG8_SA(1, 1), a1 + hstep, voffA);
;             PG8_WAIT_V(8); PG8_WAIT_L(0); PG8_BAR; PG8_MMA(0, 0, At, B0); PG8_MMA(0, 1, At, B1); PG8_BAR; PG8_SCHED;
;             PG8_LDA(At, 0, 1); PG8_STAGE(PG8_SB(0, 0), b2, voffB); PG8_STAGE(PG8_SB(0, 1), b2 + hstep, voffB); PG8_STAGE(PG8_SA(0, 0), a2, voffA);
;             PG8_WAIT_V(8); PG8_WAIT_L(0); PG8_BAR; PG8_MMA(1, 0, At, B0); PG8_MMA(1, 1, At, B1); PG8_BAR; PG8_SCHED;
.LBB0_366:
	ds_read_b128 v[130:133], v228
	ds_read_b128 v[134:137], v228 offset:1024
	ds_read_b128 v[138:141], v228 offset:2048
	ds_read_b128 v[170:173], v228 offset:3072
	ds_read_b128 v[174:177], v229
	ds_read_b128 v[178:181], v229 offset:1024
	ds_read_b128 v[182:185], v229 offset:2048
	ds_read_b128 v[186:189], v229 offset:3072
	s_add_u32 s12, s10, 0xfff00080
	s_addc_u32 s13, s11, -1
	s_cmp_eq_u32 s80, 60
	s_cselect_b32 s15, s0, s13
	s_cselect_b32 s14, s1, s12
	s_cselect_b32 s13, s61, s77
	s_cselect_b32 s12, s69, s71
	s_add_i32 m0, s79, 0xc000
	ds_read_b128 v[190:193], v230
	ds_read_b128 v[194:197], v230 offset:1024
	ds_read_b128 v[198:201], v230 offset:2048
	ds_read_b128 v[202:205], v230 offset:3072
	ds_read_b128 v[206:209], v230 offset:4096
	ds_read_b128 v[210:213], v230 offset:5120
	ds_read_b128 v[214:217], v230 offset:6144
	ds_read_b128 v[218:221], v230 offset:7168
	global_load_lds_dwordx4 v164, s[10:11]
	s_add_i32 m0, s79, 0xe000
	s_nop 0
	global_load_lds_dwordx4 v166, s[10:11]
	s_waitcnt vmcnt(8)
	s_waitcnt lgkmcnt(0)
	s_barrier
	s_setprio 1
	s_waitcnt lgkmcnt(0)
	v_mfma_f32_16x16x32_bf16 v[126:129], v[130:133], v[190:193], v[126:129]
	v_mfma_f32_16x16x32_bf16 v[126:129], v[134:137], v[194:197], v[126:129]
	v_mfma_f32_16x16x32_bf16 v[122:125], v[138:141], v[190:193], v[122:125]
	v_mfma_f32_16x16x32_bf16 v[122:125], v[170:173], v[194:197], v[122:125]
	v_mfma_f32_16x16x32_bf16 v[110:113], v[130:133], v[198:201], v[110:113]
	v_mfma_f32_16x16x32_bf16 v[110:113], v[134:137], v[202:205], v[110:113]
	v_mfma_f32_16x16x32_bf16 v[106:109], v[138:141], v[198:201], v[106:109]
	v_mfma_f32_16x16x32_bf16 v[106:109], v[170:173], v[202:205], v[106:109]
	v_mfma_f32_16x16x32_bf16 v[94:97], v[130:133], v[206:209], v[94:97]
	v_mfma_f32_16x16x32_bf16 v[94:97], v[134:137], v[210:213], v[94:97]
	v_mfma_f32_16x16x32_bf16 v[90:93], v[138:141], v[206:209], v[90:93]
	v_mfma_f32_16x16x32_bf16 v[90:93], v[170:173], v[210:213], v[90:93]
	v_mfma_f32_16x16x32_bf16 v[78:81], v[130:133], v[214:217], v[78:81]
	v_mfma_f32_16x16x32_bf16 v[78:81], v[134:137], v[218:221], v[78:81]
	v_mfma_f32_16x16x32_bf16 v[74:77], v[138:141], v[214:217], v[74:77]
	v_mfma_f32_16x16x32_bf16 v[74:77], v[170:173], v[218:221], v[74:77]
	s_setprio 0
	s_setprio 1
	v_mfma_f32_16x16x32_bf16 v[118:121], v[174:177], v[190:193], v[118:121]
	v_mfma_f32_16x16x32_bf16 v[118:121], v[178:181], v[194:197], v[118:121]
	v_mfma_f32_16x16x32_bf16 v[114:117], v[182:185], v[190:193], v[114:117]
	v_mfma_f32_16x16x32_bf16 v[114:117], v[186:189], v[194:197], v[114:117]
	v_mfma_f32_16x16x32_bf16 v[102:105], v[174:177], v[198:201], v[102:105]
	v_mfma_f32_16x16x32_bf16 v[102:105], v[178:181], v[202:205], v[102:105]
	v_mfma_f32_16x16x32_bf16 v[98:101], v[182:185], v[198:201], v[98:101]
	v_mfma_f32_16x16x32_bf16 v[98:101], v[186:189], v[202:205], v[98:101]
	v_mfma_f32_16x16x32_bf16 v[86:89], v[174:177], v[206:209], v[86:89]
	v_mfma_f32_16x16x32_bf16 v[86:89], v[178:181], v[210:213], v[86:89]
	v_mfma_f32_16x16x32_bf16 v[82:85], v[182:185], v[206:209], v[82:85]
	v_mfma_f32_16x16x32_bf16 v[82:85], v[186:189], v[210:213], v[82:85]
	v_mfma_f32_16x16x32_bf16 v[70:73], v[174:177], v[214:217], v[70:73]
	v_mfma_f32_16x16x32_bf16 v[70:73], v[178:181], v[218:221], v[70:73]
	v_mfma_f32_16x16x32_bf16 v[66:69], v[182:185], v[214:217], v[66:69]
	v_mfma_f32_16x16x32_bf16 v[66:69], v[186:189], v[218:221], v[66:69]
	s_setprio 0
	s_barrier
	s_add_i32 s81, s63, s67
	s_mov_b32 m0, s81
	ds_read_b128 v[190:193], v230 offset:16384
	ds_read_b128 v[194:197], v230 offset:17408
	ds_read_b128 v[198:201], v230 offset:18432
	ds_read_b128 v[202:205], v230 offset:19456
	ds_read_b128 v[206:209], v230 offset:20480
	ds_read_b128 v[210:213], v230 offset:21504
	ds_read_b128 v[214:217], v230 offset:22528
	ds_read_b128 v[218:221], v230 offset:23552
	global_load_lds_dwordx4 v144, s[12:13]
	s_add_i32 m0, s81, 0x2000
	s_add_u32 s82, s12, 0x100000
	s_addc_u32 s83, s13, 0
	s_add_i32 s81, s94, s67
	global_load_lds_dwordx4 v148, s[12:13]
	s_mov_b32 m0, s81
	s_nop 0
	global_load_lds_dwordx4 v144, s[82:83]
	s_add_i32 m0, s81, 0x2000
	s_nop 0
	global_load_lds_dwordx4 v148, s[82:83]
	s_mov_b32 m0, s79
	s_nop 0
	global_load_lds_dwordx4 v142, s[14:15]
	s_mov_b32 m0, s88
	s_nop 0
	global_load_lds_dwordx4 v146, s[14:15]
	s_waitcnt vmcnt(8)
	s_waitcnt lgkmcnt(0)
	s_barrier
	s_setprio 1
	s_waitcnt lgkmcnt(0)
	v_mfma_f32_16x16x32_bf16 v[62:65], v[130:133], v[190:193], v[62:65]
	v_mfma_f32_16x16x32_bf16 v[62:65], v[134:137], v[194:197], v[62:65]
	v_mfma_f32_16x16x32_bf16 v[58:61], v[138:141], v[190:193], v[58:61]
	v_mfma_f32_16x16x32_bf16 v[58:61], v[170:173], v[194:197], v[58:61]
	v_mfma_f32_16x16x32_bf16 v[46:49], v[130:133], v[198:201], v[46:49]
	v_mfma_f32_16x16x32_bf16 v[46:49], v[134:137], v[202:205], v[46:49]
	v_mfma_f32_16x16x32_bf16 v[42:45], v[138:141], v[198:201], v[42:45]
	v_mfma_f32_16x16x32_bf16 v[42:45], v[170:173], v[202:205], v[42:45]
	v_mfma_f32_16x16x32_bf16 v[30:33], v[130:133], v[206:209], v[30:33]
	v_mfma_f32_16x16x32_bf16 v[30:33], v[134:137], v[210:213], v[30:33]
	v_mfma_f32_16x16x32_bf16 v[26:29], v[138:141], v[206:209], v[26:29]
	v_mfma_f32_16x16x32_bf16 v[26:29], v[170:173], v[210:213], v[26:29]
	v_mfma_f32_16x16x32_bf16 v[14:17], v[130:133], v[214:217], v[14:17]
	v_mfma_f32_16x16x32_bf16 v[14:17], v[134:137], v[218:221], v[14:17]
	v_mfma_f32_16x16x32_bf16 v[10:13], v[138:141], v[214:217], v[10:13]
	v_mfma_f32_16x16x32_bf16 v[10:13], v[170:173], v[218:221], v[10:13]
	s_setprio 0
	s_setprio 1
	v_mfma_f32_16x16x32_bf16 v[54:57], v[174:177], v[190:193], v[54:57]
	v_mfma_f32_16x16x32_bf16 v[54:57], v[178:181], v[194:197], v[54:57]
	v_mfma_f32_16x16x32_bf16 v[50:53], v[182:185], v[190:193], v[50:53]
	v_mfma_f32_16x16x32_bf16 v[50:53], v[186:189], v[194:197], v[50:53]
	v_mfma_f32_16x16x32_bf16 v[38:41], v[174:177], v[198:201], v[38:41]
	v_mfma_f32_16x16x32_bf16 v[38:41], v[178:181], v[202:205], v[38:41]
	v_mfma_f32_16x16x32_bf16 v[34:37], v[182:185], v[198:201], v[34:37]
	v_mfma_f32_16x16x32_bf16 v[34:37], v[186:189], v[202:205], v[34:37]
	v_mfma_f32_16x16x32_bf16 v[22:25], v[174:177], v[206:209], v[22:25]
	v_mfma_f32_16x16x32_bf16 v[22:25], v[178:181], v[210:213], v[22:25]
	v_mfma_f32_16x16x32_bf16 v[18:21], v[182:185], v[206:209], v[18:21]
	v_mfma_f32_16x16x32_bf16 v[18:21], v[186:189], v[210:213], v[18:21]
	v_mfma_f32_16x16x32_bf16 v[6:9], v[174:177], v[214:217], v[6:9]
	v_mfma_f32_16x16x32_bf16 v[6:9], v[178:181], v[218:221], v[6:9]
	v_mfma_f32_16x16x32_bf16 v[2:5], v[182:185], v[214:217], v[2:5]
	v_mfma_f32_16x16x32_bf16 v[2:5], v[186:189], v[218:221], v[2:5]
	s_setprio 0
	s_barrier
; #define PG8_STAGE(bufoff, gbase, voff) do { _Pragma("unroll") for (int _i = 0; _i < 2; ++_i) \
;         __builtin_amdgcn_global_load_lds((const unsigned*)((const char*)(gbase) + (voff)[_i]), (PG8_LAS unsigned*)(lds + (bufoff) + ldsw + _i * 8192), 16, 0, 0); } while (0)
; #define PG8_LDA(dst, b, h) do { _Pragma("unroll") for (int m = 0; m < 4; ++m) _Pragma("unroll") for (int k = 0; k < 2; ++k) dst[m][k] = *(const PG8_LAS bf16x8*)(lds + PG8_SA(b, h) + aoff + m * 2048 + k * 1024); } while (0)
; #define PG8_LDB(dst, b, h) do { _Pragma("unroll") for (int n = 0; n < 2; ++n) _Pragma("unroll") for (int k = 0; k < 2; ++k) dst[n][k] = *(const PG8_LAS bf16x8*)(lds + PG8_SB(b, h) + boff + n * 2048 + k * 1024); } while (0)
; #define PG8_MMA(ai, bj, At, Bt) do { __builtin_amdgcn_s_setprio(1); _Pragma("unroll") for (int m = 0; m < 4; ++m) _Pragma("unroll") for (int n = 0; n < 2; ++n) _Pragma("unroll") for (int k = 0; k < 2; ++k) \
;         acc[ai][bj][m][n] = __builtin_amdgcn_mfma_f32_16x16x32_bf16(Bt[n][k], At[m][k], acc[ai][bj][m][n], 0, 0, 0); __builtin_amdgcn_s_setprio(0); } while (0)
; #define PG8_WAIT_V(n) asm volatile("s_waitcnt vmcnt(" #n ")" ::: "memory")
; #define PG8_WAIT_L(n) asm volatile("s_waitcnt lgkmcnt(" #n ")" ::: "memory")
; #define PG8_BAR __builtin_amdgcn_s_barrier()
; #define PG8_SCHED __builtin_amdgcn_sched_barrier(0)
; template <class Epi, class Sched, bool ALIGN_EPI = false, bool SP2 = false>
; __device__ __forceinline__ void gemm_phase(PG8_LAS unsigned char* lds, const Gemm g, const Sched& S, const Epi& E) {
;     ...
;             PG8_LDB(B0, 1, 0); PG8_LDB(B1, 1, 1); PG8_SCHED; PG8_LDA(At, 1, 0); PG8_STAGE(PG8_SA(0, 1), a2 + hstep, voffA);
;             PG8_WAIT_V(8); PG8_WAIT_L(0); PG8_BAR; PG8_MMA(0, 0, At, B0); PG8_MMA(0, 1, At, B1); PG8_BAR; PG8_SCHED;
;             PG8_LDA(At, 1, 1); PG8_STAGE(PG8_SB(1, 0), b3, voffB); PG8_STAGE(PG8_SB(1, 1), b3 + hstep, voffB); PG8_STAGE(PG8_SA(1, 0), a3, voffA);
;             PG8_WAIT_V(8); PG8_WAIT_L(0); PG8_BAR; PG8_MMA(1, 0, At, B0); PG8_MMA(1, 1, At, B1); PG8_BAR; PG8_SCHED;
	s_add_i32 s81, 0, 0x18000
	v_add_u32_e32 v150, s81, v153
	s_add_i32 s82, 0, 0x1c000
	ds_read_b128 v[130:133], v150
	ds_read_b128 v[134:137], v150 offset:1024
	ds_read_b128 v[138:141], v150 offset:2048
	ds_read_b128 v[170:173], v150 offset:3072
	v_add_u32_e32 v150, s82, v153
	ds_read_b128 v[174:177], v150
	ds_read_b128 v[178:181], v150 offset:1024
	ds_read_b128 v[182:185], v150 offset:2048
	ds_read_b128 v[186:189], v150 offset:3072
	s_add_u32 s14, s14, 0x100000
	s_addc_u32 s15, s15, 0
	s_mov_b32 m0, s89
	ds_read_b128 v[190:193], v230 offset:32768
	ds_read_b128 v[194:197], v230 offset:33792
	ds_read_b128 v[198:201], v230 offset:34816
	ds_read_b128 v[202:205], v230 offset:35840
	ds_read_b128 v[206:209], v230 offset:36864
	ds_read_b128 v[210:213], v230 offset:37888
	ds_read_b128 v[214:217], v230 offset:38912
	ds_read_b128 v[218:221], v230 offset:39936
	global_load_lds_dwordx4 v142, s[14:15]
	s_mov_b32 m0, s90
	s_nop 0
	global_load_lds_dwordx4 v146, s[14:15]
	s_waitcnt vmcnt(8)
	s_waitcnt lgkmcnt(0)
	s_barrier
	s_setprio 1
	s_waitcnt lgkmcnt(0)
	v_mfma_f32_16x16x32_bf16 v[126:129], v[130:133], v[190:193], v[126:129]
	v_mfma_f32_16x16x32_bf16 v[126:129], v[134:137], v[194:197], v[126:129]
	v_mfma_f32_16x16x32_bf16 v[122:125], v[138:141], v[190:193], v[122:125]
	v_mfma_f32_16x16x32_bf16 v[122:125], v[170:173], v[194:197], v[122:125]
	v_mfma_f32_16x16x32_bf16 v[110:113], v[130:133], v[198:201], v[110:113]
	v_mfma_f32_16x16x32_bf16 v[110:113], v[134:137], v[202:205], v[110:113]
	v_mfma_f32_16x16x32_bf16 v[106:109], v[138:141], v[198:201], v[106:109]
	v_mfma_f32_16x16x32_bf16 v[106:109], v[170:173], v[202:205], v[106:109]
	v_mfma_f32_16x16x32_bf16 v[94:97], v[130:133], v[206:209], v[94:97]
	v_mfma_f32_16x16x32_bf16 v[94:97], v[134:137], v[210:213], v[94:97]
	v_mfma_f32_16x16x32_bf16 v[90:93], v[138:141], v[206:209], v[90:93]
	v_mfma_f32_16x16x32_bf16 v[90:93], v[170:173], v[210:213], v[90:93]
	v_mfma_f32_16x16x32_bf16 v[78:81], v[130:133], v[214:217], v[78:81]
	v_mfma_f32_16x16x32_bf16 v[78:81], v[134:137], v[218:221], v[78:81]
	v_mfma_f32_16x16x32_bf16 v[74:77], v[138:141], v[214:217], v[74:77]
	v_mfma_f32_16x16x32_bf16 v[74:77], v[170:173], v[218:221], v[74:77]
	s_setprio 0
	s_setprio 1
	v_mfma_f32_16x16x32_bf16 v[118:121], v[174:177], v[190:193], v[118:121]
	v_mfma_f32_16x16x32_bf16 v[118:121], v[178:181], v[194:197], v[118:121]
	v_mfma_f32_16x16x32_bf16 v[114:117], v[182:185], v[190:193], v[114:117]
	v_mfma_f32_16x16x32_bf16 v[114:117], v[186:189], v[194:197], v[114:117]
	v_mfma_f32_16x16x32_bf16 v[102:105], v[174:177], v[198:201], v[102:105]
	v_mfma_f32_16x16x32_bf16 v[102:105], v[178:181], v[202:205], v[102:105]
	v_mfma_f32_16x16x32_bf16 v[98:101], v[182:185], v[198:201], v[98:101]
	v_mfma_f32_16x16x32_bf16 v[98:101], v[186:189], v[202:205], v[98:101]
	v_mfma_f32_16x16x32_bf16 v[86:89], v[174:177], v[206:209], v[86:89]
	v_mfma_f32_16x16x32_bf16 v[86:89], v[178:181], v[210:213], v[86:89]
	v_mfma_f32_16x16x32_bf16 v[82:85], v[182:185], v[206:209], v[82:85]
	v_mfma_f32_16x16x32_bf16 v[82:85], v[186:189], v[210:213], v[82:85]
	v_mfma_f32_16x16x32_bf16 v[70:73], v[174:177], v[214:217], v[70:73]
	v_mfma_f32_16x16x32_bf16 v[70:73], v[178:181], v[218:221], v[70:73]
	v_mfma_f32_16x16x32_bf16 v[66:69], v[182:185], v[214:217], v[66:69]
	v_mfma_f32_16x16x32_bf16 v[66:69], v[186:189], v[218:221], v[66:69]
	s_setprio 0
	s_barrier
	s_add_u32 s100, s14, 0xfff00080
	s_addc_u32 s101, s15, -1
	s_add_u32 s98, s12, 0x80
	s_addc_u32 s99, s13, 0
	s_add_i32 s14, s81, s67
	s_mov_b32 m0, s14
	ds_read_b128 v[190:193], v230 offset:49152
	ds_read_b128 v[194:197], v230 offset:50176
	ds_read_b128 v[198:201], v230 offset:51200
	ds_read_b128 v[202:205], v230 offset:52224
	ds_read_b128 v[206:209], v230 offset:53248
	ds_read_b128 v[210:213], v230 offset:54272
	ds_read_b128 v[214:217], v230 offset:55296
	ds_read_b128 v[218:221], v230 offset:56320
	global_load_lds_dwordx4 v144, s[98:99]
	s_add_i32 m0, s14, 0x2000
	s_add_u32 s12, s12, 0x100080
	s_addc_u32 s13, s13, 0
	s_add_i32 s14, s82, s67
	global_load_lds_dwordx4 v148, s[98:99]
	s_mov_b32 m0, s14
	s_nop 0
	global_load_lds_dwordx4 v144, s[12:13]
	s_add_i32 m0, s14, 0x2000
	s_nop 0
	global_load_lds_dwordx4 v148, s[12:13]
	s_mov_b32 m0, s93
	s_nop 0
	global_load_lds_dwordx4 v142, s[100:101]
	s_mov_b32 m0, s62
	s_nop 0
	global_load_lds_dwordx4 v146, s[100:101]
	s_waitcnt vmcnt(8)
	s_waitcnt lgkmcnt(0)
	s_barrier
	s_setprio 1
	s_waitcnt lgkmcnt(0)
	v_mfma_f32_16x16x32_bf16 v[62:65], v[130:133], v[190:193], v[62:65]
	v_mfma_f32_16x16x32_bf16 v[62:65], v[134:137], v[194:197], v[62:65]
	v_mfma_f32_16x16x32_bf16 v[58:61], v[138:141], v[190:193], v[58:61]
	v_mfma_f32_16x16x32_bf16 v[58:61], v[170:173], v[194:197], v[58:61]
	v_mfma_f32_16x16x32_bf16 v[46:49], v[130:133], v[198:201], v[46:49]
	v_mfma_f32_16x16x32_bf16 v[46:49], v[134:137], v[202:205], v[46:49]
	v_mfma_f32_16x16x32_bf16 v[42:45], v[138:141], v[198:201], v[42:45]
	v_mfma_f32_16x16x32_bf16 v[42:45], v[170:173], v[202:205], v[42:45]
	v_mfma_f32_16x16x32_bf16 v[30:33], v[130:133], v[206:209], v[30:33]
	v_mfma_f32_16x16x32_bf16 v[30:33], v[134:137], v[210:213], v[30:33]
	v_mfma_f32_16x16x32_bf16 v[26:29], v[138:141], v[206:209], v[26:29]
	v_mfma_f32_16x16x32_bf16 v[26:29], v[170:173], v[210:213], v[26:29]
	v_mfma_f32_16x16x32_bf16 v[14:17], v[130:133], v[214:217], v[14:17]
	v_mfma_f32_16x16x32_bf16 v[14:17], v[134:137], v[218:221], v[14:17]
	v_mfma_f32_16x16x32_bf16 v[10:13], v[138:141], v[214:217], v[10:13]
	v_mfma_f32_16x16x32_bf16 v[10:13], v[170:173], v[218:221], v[10:13]
	s_setprio 0
	s_setprio 1
	v_mfma_f32_16x16x32_bf16 v[54:57], v[174:177], v[190:193], v[54:57]
	v_mfma_f32_16x16x32_bf16 v[54:57], v[178:181], v[194:197], v[54:57]
	v_mfma_f32_16x16x32_bf16 v[50:53], v[182:185], v[190:193], v[50:53]
	v_mfma_f32_16x16x32_bf16 v[50:53], v[186:189], v[194:197], v[50:53]
	v_mfma_f32_16x16x32_bf16 v[38:41], v[174:177], v[198:201], v[38:41]
	v_mfma_f32_16x16x32_bf16 v[38:41], v[178:181], v[202:205], v[38:41]
	v_mfma_f32_16x16x32_bf16 v[34:37], v[182:185], v[198:201], v[34:37]
	v_mfma_f32_16x16x32_bf16 v[34:37], v[186:189], v[202:205], v[34:37]
	v_mfma_f32_16x16x32_bf16 v[22:25], v[174:177], v[206:209], v[22:25]
	v_mfma_f32_16x16x32_bf16 v[22:25], v[178:181], v[210:213], v[22:25]
	v_mfma_f32_16x16x32_bf16 v[18:21], v[182:185], v[206:209], v[18:21]
	v_mfma_f32_16x16x32_bf16 v[18:21], v[186:189], v[210:213], v[18:21]
	v_mfma_f32_16x16x32_bf16 v[6:9], v[174:177], v[214:217], v[6:9]
	v_mfma_f32_16x16x32_bf16 v[6:9], v[178:181], v[218:221], v[6:9]
	v_mfma_f32_16x16x32_bf16 v[2:5], v[182:185], v[214:217], v[2:5]
	v_mfma_f32_16x16x32_bf16 v[2:5], v[186:189], v[218:221], v[2:5]
	s_setprio 0
	s_barrier
	s_add_i32 s80, s80, 2
	s_add_u32 s10, s10, 0x100
	s_addc_u32 s11, s11, 0
	s_add_u32 s71, s71, 0x100
	s_addc_u32 s77, s77, 0
	s_cmp_gt_u32 s80, 61
	s_cbranch_scc0 .LBB0_366
	s_and_b64 vcc, exec, s[28:29]
	s_cbranch_vccz .LBB0_369
	s_barrier

; #define PG8_STAGE(bufoff, gbase, voff) do { _Pragma("unroll") for (int _i = 0; _i < 2; ++_i) \
;         __builtin_amdgcn_global_load_lds((const unsigned*)((const char*)(gbase) + (voff)[_i]), (PG8_LAS unsigned*)(lds + (bufoff) + ldsw + _i * 8192), 16, 0, 0); } while (0)
; #define PG8_LDA(dst, b, h) do { _Pragma("unroll") for (int m = 0; m < 4; ++m) _Pragma("unroll") for (int k = 0; k < 2; ++k) dst[m][k] = *(const PG8_LAS bf16x8*)(lds + PG8_SA(b, h) + aoff + m * 2048 + k * 1024); } while (0)
; #define PG8_LDB(dst, b, h) do { _Pragma("unroll") for (int n = 0; n < 2; ++n) _Pragma("unroll") for (int k = 0; k < 2; ++k) dst[n][k] = *(const PG8_LAS bf16x8*)(lds + PG8_SB(b, h) + boff + n * 2048 + k * 1024); } while (0)
; #define PG8_MMA(ai, bj, At, Bt) do { __builtin_amdgcn_s_setprio(1); _Pragma("unroll") for (int m = 0; m < 4; ++m) _Pragma("unroll") for (int n = 0; n < 2; ++n) _Pragma("unroll") for (int k = 0; k < 2; ++k) \
;         acc[ai][bj][m][n] = __builtin_amdgcn_mfma_f32_16x16x32_bf16(Bt[n][k], At[m][k], acc[ai][bj][m][n], 0, 0, 0); __builtin_amdgcn_s_setprio(0); } while (0)
; #define PG8_WAIT_V(n) asm volatile("s_waitcnt vmcnt(" #n ")" ::: "memory")
; #define PG8_WAIT_L(n) asm volatile("s_waitcnt lgkmcnt(" #n ")" ::: "memory")
; #define PG8_BAR __builtin_amdgcn_s_barrier()
; template <class Epi, class Sched, bool ALIGN_EPI = false, bool SP2 = false>
; __device__ __forceinline__ void gemm_phase(PG8_LAS unsigned char* lds, const Gemm g, const Sched& S, const Epi& E) {
;     ...
;             const char* a1 = cA + (size_t)(t + 1) * kstep;
;             const char* a2 = last ? nA : cA + (size_t)(t + 2) * kstep; const char* b2 = last ? nB : cB + (size_t)(t + 2) * kstep;
;             const char* a3 = a2 + kstep; const char* b3 = b2 + kstep;
;             if (last && has_next) S.a_ready(nxt);
;             if constexpr (SP2) {
;             PG8_LDB(B0, 0, 0); PG8_LDB(B1, 0, 1); PG8_SCHED; PG8_LDA(At, 0, 0); PG8_STAGE(PG8_SA(1, 1), a1 + hstep, voffA);
;             PG8_WAIT_V(8); PG8_WAIT_L(0); PG8_BAR; PG8_MMA(0, 0, At, B0); PG8_MMA(0, 1, At, B1); PG8_BAR; PG8_SCHED;
;             PG8_LDA(At, 0, 1); PG8_STAGE(PG8_SB(0, 0), b2, voffB); PG8_STAGE(PG8_SB(0, 1), b2 + hstep, voffB); PG8_STAGE(PG8_SA(0, 0), a2, voffA);
;             PG8_WAIT_V(8); PG8_WAIT_L(0); PG8_BAR; PG8_MMA(1, 0, At, B0); PG8_MMA(1, 1, At, B1); PG8_BAR; PG8_SCHED;
.LBB0_2487:
	v_add_u32_e32 v3, s67, v183
	s_add_i32 s81, s50, 2
	ds_read_b128 v[154:157], v3
	ds_read_b128 v[158:161], v3 offset:1024
	ds_read_b128 v[162:165], v3 offset:2048
	ds_read_b128 v[166:169], v3 offset:3072
	v_add_u32_e32 v3, s68, v183
	s_add_u32 s51, s42, s46
	ds_read_b128 v[170:173], v3
	ds_read_b128 v[174:177], v3 offset:1024
	ds_read_b128 v[178:181], v3 offset:2048
	ds_read_b128 v[184:187], v3 offset:3072
	s_addc_u32 s52, s43, s47
	s_add_u32 s51, s51, 0x100
	s_addc_u32 s52, s52, 0
	s_add_u32 s82, s79, s46
	s_addc_u32 s83, s80, s47
	s_cmp_eq_u32 s9, s50
	s_cselect_b32 s53, s27, s52
	s_cselect_b32 s52, s35, s51
	s_cselect_b32 s51, s31, s83
	s_cselect_b32 s50, s78, s82
	v_lshl_add_u64 v[4:5], v[150:151], 0, s[46:47]
	s_add_i32 m0, s11, 0xc000
	ds_read_b128 v[188:191], v211
	ds_read_b128 v[192:195], v211 offset:1024
	ds_read_b128 v[196:199], v211 offset:2048
	ds_read_b128 v[200:203], v211 offset:3072
	ds_read_b128 v[204:207], v211 offset:4096
	ds_read_b128 v[212:215], v211 offset:5120
	ds_read_b128 v[216:219], v211 offset:6144
	ds_read_b128 v[220:223], v211 offset:7168
	global_load_lds_dwordx4 v[4:5], off
	v_lshl_add_u64 v[4:5], v[152:153], 0, s[46:47]
	s_add_i32 m0, s11, 0xe000
	s_nop 0
	global_load_lds_dwordx4 v[4:5], off
	s_waitcnt vmcnt(8)
	s_waitcnt lgkmcnt(0)
	s_barrier
	s_setprio 1
	s_waitcnt lgkmcnt(0)
	v_mfma_f32_16x16x32_bf16 v[130:133], v[154:157], v[188:191], v[130:133]
	v_mfma_f32_16x16x32_bf16 v[130:133], v[158:161], v[192:195], v[130:133]
	v_mfma_f32_16x16x32_bf16 v[126:129], v[162:165], v[188:191], v[126:129]
	v_mfma_f32_16x16x32_bf16 v[126:129], v[166:169], v[192:195], v[126:129]
	v_mfma_f32_16x16x32_bf16 v[114:117], v[154:157], v[196:199], v[114:117]
	v_mfma_f32_16x16x32_bf16 v[114:117], v[158:161], v[200:203], v[114:117]
	v_mfma_f32_16x16x32_bf16 v[110:113], v[162:165], v[196:199], v[110:113]
	v_mfma_f32_16x16x32_bf16 v[110:113], v[166:169], v[200:203], v[110:113]
	v_mfma_f32_16x16x32_bf16 v[98:101], v[154:157], v[204:207], v[98:101]
	v_mfma_f32_16x16x32_bf16 v[98:101], v[158:161], v[212:215], v[98:101]
	v_mfma_f32_16x16x32_bf16 v[94:97], v[162:165], v[204:207], v[94:97]
	v_mfma_f32_16x16x32_bf16 v[94:97], v[166:169], v[212:215], v[94:97]
	v_mfma_f32_16x16x32_bf16 v[82:85], v[154:157], v[216:219], v[82:85]
	v_mfma_f32_16x16x32_bf16 v[82:85], v[158:161], v[220:223], v[82:85]
	v_mfma_f32_16x16x32_bf16 v[78:81], v[162:165], v[216:219], v[78:81]
	v_mfma_f32_16x16x32_bf16 v[78:81], v[166:169], v[220:223], v[78:81]
	s_setprio 0
	s_setprio 1
	v_mfma_f32_16x16x32_bf16 v[122:125], v[170:173], v[188:191], v[122:125]
	v_mfma_f32_16x16x32_bf16 v[122:125], v[174:177], v[192:195], v[122:125]
	v_mfma_f32_16x16x32_bf16 v[118:121], v[178:181], v[188:191], v[118:121]
	v_mfma_f32_16x16x32_bf16 v[118:121], v[184:187], v[192:195], v[118:121]
	v_mfma_f32_16x16x32_bf16 v[106:109], v[170:173], v[196:199], v[106:109]
	v_mfma_f32_16x16x32_bf16 v[106:109], v[174:177], v[200:203], v[106:109]
	v_mfma_f32_16x16x32_bf16 v[102:105], v[178:181], v[196:199], v[102:105]
	v_mfma_f32_16x16x32_bf16 v[102:105], v[184:187], v[200:203], v[102:105]
	v_mfma_f32_16x16x32_bf16 v[90:93], v[170:173], v[204:207], v[90:93]
	v_mfma_f32_16x16x32_bf16 v[90:93], v[174:177], v[212:215], v[90:93]
	v_mfma_f32_16x16x32_bf16 v[86:89], v[178:181], v[204:207], v[86:89]
	v_mfma_f32_16x16x32_bf16 v[86:89], v[184:187], v[212:215], v[86:89]
	v_mfma_f32_16x16x32_bf16 v[74:77], v[170:173], v[216:219], v[74:77]
	v_mfma_f32_16x16x32_bf16 v[74:77], v[174:177], v[220:223], v[74:77]
	v_mfma_f32_16x16x32_bf16 v[70:73], v[178:181], v[216:219], v[70:73]
	v_mfma_f32_16x16x32_bf16 v[70:73], v[184:187], v[220:223], v[70:73]
	s_setprio 0
	s_barrier
	s_add_i32 s82, s67, s55
	s_mov_b32 m0, s82
	ds_read_b128 v[188:191], v211 offset:16384
	ds_read_b128 v[192:195], v211 offset:17408
	ds_read_b128 v[196:199], v211 offset:18432
	ds_read_b128 v[200:203], v211 offset:19456
	ds_read_b128 v[204:207], v211 offset:20480
	ds_read_b128 v[212:215], v211 offset:21504
	ds_read_b128 v[216:219], v211 offset:22528
	ds_read_b128 v[220:223], v211 offset:23552
	global_load_lds_dwordx4 v134, s[50:51]
	s_add_i32 m0, s82, 0x2000
	s_add_u32 s82, s50, 0x100000
	s_addc_u32 s83, s51, 0
	s_add_i32 s84, s68, s55
	global_load_lds_dwordx4 v136, s[50:51]
	s_mov_b32 m0, s84
	s_nop 0
	global_load_lds_dwordx4 v134, s[82:83]
	s_add_i32 m0, s84, 0x2000
	s_nop 0
	global_load_lds_dwordx4 v136, s[82:83]
	s_mov_b32 m0, s11
	s_nop 0
	global_load_lds_dwordx4 v134, s[52:53]
	s_mov_b32 m0, s57
	s_nop 0
	global_load_lds_dwordx4 v136, s[52:53]
	s_waitcnt vmcnt(8)
	s_waitcnt lgkmcnt(0)
	s_barrier
; #define PG8_STAGE(bufoff, gbase, voff) do { _Pragma("unroll") for (int _i = 0; _i < 2; ++_i) \
;         __builtin_amdgcn_global_load_lds((const unsigned*)((const char*)(gbase) + (voff)[_i]), (PG8_LAS unsigned*)(lds + (bufoff) + ldsw + _i * 8192), 16, 0, 0); } while (0)
; #define PG8_LDA(dst, b, h) do { _Pragma("unroll") for (int m = 0; m < 4; ++m) _Pragma("unroll") for (int k = 0; k < 2; ++k) dst[m][k] = *(const PG8_LAS bf16x8*)(lds + PG8_SA(b, h) + aoff + m * 2048 + k * 1024); } while (0)
; #define PG8_LDB(dst, b, h) do { _Pragma("unroll") for (int n = 0; n < 2; ++n) _Pragma("unroll") for (int k = 0; k < 2; ++k) dst[n][k] = *(const PG8_LAS bf16x8*)(lds + PG8_SB(b, h) + boff + n * 2048 + k * 1024); } while (0)
; #define PG8_MMA(ai, bj, At, Bt) do { __builtin_amdgcn_s_setprio(1); _Pragma("unroll") for (int m = 0; m < 4; ++m) _Pragma("unroll") for (int n = 0; n < 2; ++n) _Pragma("unroll") for (int k = 0; k < 2; ++k) \
;         acc[ai][bj][m][n] = __builtin_amdgcn_mfma_f32_16x16x32_bf16(Bt[n][k], At[m][k], acc[ai][bj][m][n], 0, 0, 0); __builtin_amdgcn_s_setprio(0); } while (0)
; #define PG8_WAIT_V(n) asm volatile("s_waitcnt vmcnt(" #n ")" ::: "memory")
; #define PG8_WAIT_L(n) asm volatile("s_waitcnt lgkmcnt(" #n ")" ::: "memory")
; #define PG8_BAR __builtin_amdgcn_s_barrier()
; #define PG8_SCHED __builtin_amdgcn_sched_barrier(0)
; template <class Epi, class Sched, bool ALIGN_EPI = false, bool SP2 = false>
; __device__ __forceinline__ void gemm_phase(PG8_LAS unsigned char* lds, const Gemm g, const Sched& S, const Epi& E) {
;     ...
;             PG8_WAIT_V(8); PG8_WAIT_L(0); PG8_BAR; PG8_MMA(1, 0, At, B0); PG8_MMA(1, 1, At, B1); PG8_BAR; PG8_SCHED;
;             PG8_LDB(B0, 1, 0); PG8_LDB(B1, 1, 1); PG8_SCHED; PG8_LDA(At, 1, 0); PG8_STAGE(PG8_SA(0, 1), a2 + hstep, voffA);
;             PG8_WAIT_V(8); PG8_WAIT_L(0); PG8_BAR; PG8_MMA(0, 0, At, B0); PG8_MMA(0, 1, At, B1); PG8_BAR; PG8_SCHED;
	s_setprio 1
	s_waitcnt lgkmcnt(0)
	v_mfma_f32_16x16x32_bf16 v[66:69], v[154:157], v[188:191], v[66:69]
	v_mfma_f32_16x16x32_bf16 v[66:69], v[158:161], v[192:195], v[66:69]
	v_mfma_f32_16x16x32_bf16 v[62:65], v[162:165], v[188:191], v[62:65]
	v_mfma_f32_16x16x32_bf16 v[62:65], v[166:169], v[192:195], v[62:65]
	v_mfma_f32_16x16x32_bf16 v[50:53], v[154:157], v[196:199], v[50:53]
	v_mfma_f32_16x16x32_bf16 v[50:53], v[158:161], v[200:203], v[50:53]
	v_mfma_f32_16x16x32_bf16 v[46:49], v[162:165], v[196:199], v[46:49]
	v_mfma_f32_16x16x32_bf16 v[46:49], v[166:169], v[200:203], v[46:49]
	v_mfma_f32_16x16x32_bf16 v[34:37], v[154:157], v[204:207], v[34:37]
	v_mfma_f32_16x16x32_bf16 v[34:37], v[158:161], v[212:215], v[34:37]
	v_mfma_f32_16x16x32_bf16 v[30:33], v[162:165], v[204:207], v[30:33]
	v_mfma_f32_16x16x32_bf16 v[30:33], v[166:169], v[212:215], v[30:33]
	v_mfma_f32_16x16x32_bf16 v[18:21], v[154:157], v[216:219], v[18:21]
	v_mfma_f32_16x16x32_bf16 v[18:21], v[158:161], v[220:223], v[18:21]
	v_mfma_f32_16x16x32_bf16 v[14:17], v[162:165], v[216:219], v[14:17]
	v_mfma_f32_16x16x32_bf16 v[14:17], v[166:169], v[220:223], v[14:17]
	s_setprio 0
	s_setprio 1
	v_mfma_f32_16x16x32_bf16 v[58:61], v[170:173], v[188:191], v[58:61]
	v_mfma_f32_16x16x32_bf16 v[54:57], v[178:181], v[188:191], v[54:57]
	v_mfma_f32_16x16x32_bf16 v[42:45], v[170:173], v[196:199], v[42:45]
	v_mfma_f32_16x16x32_bf16 v[38:41], v[178:181], v[196:199], v[38:41]
	v_mfma_f32_16x16x32_bf16 v[26:29], v[170:173], v[204:207], v[26:29]
	v_mfma_f32_16x16x32_bf16 v[22:25], v[178:181], v[204:207], v[22:25]
	v_mfma_f32_16x16x32_bf16 v[10:13], v[170:173], v[216:219], v[10:13]
	v_mfma_f32_16x16x32_bf16 v[4:7], v[178:181], v[216:219], v[6:9]
	v_mfma_f32_16x16x32_bf16 v[58:61], v[174:177], v[192:195], v[58:61]
	v_mfma_f32_16x16x32_bf16 v[54:57], v[184:187], v[192:195], v[54:57]
	v_mfma_f32_16x16x32_bf16 v[42:45], v[174:177], v[200:203], v[42:45]
	v_mfma_f32_16x16x32_bf16 v[38:41], v[184:187], v[200:203], v[38:41]
	v_mfma_f32_16x16x32_bf16 v[26:29], v[174:177], v[212:215], v[26:29]
	v_mfma_f32_16x16x32_bf16 v[22:25], v[184:187], v[212:215], v[22:25]
	v_mfma_f32_16x16x32_bf16 v[10:13], v[174:177], v[220:223], v[10:13]
	v_mfma_f32_16x16x32_bf16 v[4:7], v[184:187], v[220:223], v[4:7]
	s_setprio 0
	s_barrier
	s_add_i32 s82, 0, 0x18000
	v_add_u32_e32 v3, s82, v183
	s_add_i32 s83, 0, 0x1c000
	ds_read_b128 v[154:157], v3
	ds_read_b128 v[158:161], v3 offset:1024
	ds_read_b128 v[162:165], v3 offset:2048
	ds_read_b128 v[166:169], v3 offset:3072
	v_add_u32_e32 v3, s83, v183
	ds_read_b128 v[170:173], v3
	ds_read_b128 v[174:177], v3 offset:1024
	ds_read_b128 v[178:181], v3 offset:2048
	ds_read_b128 v[184:187], v3 offset:3072
	s_add_u32 s52, s52, 0x100000
	s_addc_u32 s53, s53, 0
	s_mov_b32 m0, s60
	ds_read_b128 v[188:191], v211 offset:32768
	ds_read_b128 v[192:195], v211 offset:33792
	ds_read_b128 v[196:199], v211 offset:34816
	ds_read_b128 v[200:203], v211 offset:35840
	ds_read_b128 v[204:207], v211 offset:36864
	ds_read_b128 v[212:215], v211 offset:37888
	ds_read_b128 v[216:219], v211 offset:38912
	ds_read_b128 v[220:223], v211 offset:39936
	global_load_lds_dwordx4 v134, s[52:53]
	s_mov_b32 m0, s61
	s_nop 0
	global_load_lds_dwordx4 v136, s[52:53]
	s_waitcnt vmcnt(8)
	s_waitcnt lgkmcnt(0)
	s_barrier
	s_setprio 1
	s_waitcnt lgkmcnt(0)
	v_mfma_f32_16x16x32_bf16 v[130:133], v[154:157], v[188:191], v[130:133]
	v_mfma_f32_16x16x32_bf16 v[130:133], v[158:161], v[192:195], v[130:133]
	v_mfma_f32_16x16x32_bf16 v[126:129], v[162:165], v[188:191], v[126:129]
	v_mfma_f32_16x16x32_bf16 v[126:129], v[166:169], v[192:195], v[126:129]
	v_mfma_f32_16x16x32_bf16 v[114:117], v[154:157], v[196:199], v[114:117]
	v_mfma_f32_16x16x32_bf16 v[114:117], v[158:161], v[200:203], v[114:117]
	v_mfma_f32_16x16x32_bf16 v[110:113], v[162:165], v[196:199], v[110:113]
	v_mfma_f32_16x16x32_bf16 v[110:113], v[166:169], v[200:203], v[110:113]
	v_mfma_f32_16x16x32_bf16 v[98:101], v[154:157], v[204:207], v[98:101]
	v_mfma_f32_16x16x32_bf16 v[98:101], v[158:161], v[212:215], v[98:101]
	v_mfma_f32_16x16x32_bf16 v[94:97], v[162:165], v[204:207], v[94:97]
	v_mfma_f32_16x16x32_bf16 v[94:97], v[166:169], v[212:215], v[94:97]
	v_mfma_f32_16x16x32_bf16 v[82:85], v[154:157], v[216:219], v[82:85]
	v_mfma_f32_16x16x32_bf16 v[82:85], v[158:161], v[220:223], v[82:85]
	v_mfma_f32_16x16x32_bf16 v[78:81], v[162:165], v[216:219], v[78:81]
	v_mfma_f32_16x16x32_bf16 v[78:81], v[166:169], v[220:223], v[78:81]
	s_setprio 0
	s_setprio 1
	v_mfma_f32_16x16x32_bf16 v[122:125], v[170:173], v[188:191], v[122:125]
	v_mfma_f32_16x16x32_bf16 v[122:125], v[174:177], v[192:195], v[122:125]
	v_mfma_f32_16x16x32_bf16 v[118:121], v[178:181], v[188:191], v[118:121]
	v_mfma_f32_16x16x32_bf16 v[118:121], v[184:187], v[192:195], v[118:121]
	v_mfma_f32_16x16x32_bf16 v[106:109], v[170:173], v[196:199], v[106:109]
	v_mfma_f32_16x16x32_bf16 v[106:109], v[174:177], v[200:203], v[106:109]
	v_mfma_f32_16x16x32_bf16 v[102:105], v[178:181], v[196:199], v[102:105]
	v_mfma_f32_16x16x32_bf16 v[102:105], v[184:187], v[200:203], v[102:105]
	v_mfma_f32_16x16x32_bf16 v[90:93], v[170:173], v[204:207], v[90:93]
	v_mfma_f32_16x16x32_bf16 v[90:93], v[174:177], v[212:215], v[90:93]
	v_mfma_f32_16x16x32_bf16 v[86:89], v[178:181], v[204:207], v[86:89]
	v_mfma_f32_16x16x32_bf16 v[86:89], v[184:187], v[212:215], v[86:89]
	v_mfma_f32_16x16x32_bf16 v[74:77], v[170:173], v[216:219], v[74:77]
	v_mfma_f32_16x16x32_bf16 v[74:77], v[174:177], v[220:223], v[74:77]
	v_mfma_f32_16x16x32_bf16 v[70:73], v[178:181], v[216:219], v[70:73]
	v_mfma_f32_16x16x32_bf16 v[70:73], v[184:187], v[220:223], v[70:73]
	s_setprio 0
	s_barrier
; #define PG8_STAGE(bufoff, gbase, voff) do { _Pragma("unroll") for (int _i = 0; _i < 2; ++_i) \
;         __builtin_amdgcn_global_load_lds((const unsigned*)((const char*)(gbase) + (voff)[_i]), (PG8_LAS unsigned*)(lds + (bufoff) + ldsw + _i * 8192), 16, 0, 0); } while (0)
; #define PG8_LDA(dst, b, h) do { _Pragma("unroll") for (int m = 0; m < 4; ++m) _Pragma("unroll") for (int k = 0; k < 2; ++k) dst[m][k] = *(const PG8_LAS bf16x8*)(lds + PG8_SA(b, h) + aoff + m * 2048 + k * 1024); } while (0)
; #define PG8_MMA(ai, bj, At, Bt) do { __builtin_amdgcn_s_setprio(1); _Pragma("unroll") for (int m = 0; m < 4; ++m) _Pragma("unroll") for (int n = 0; n < 2; ++n) _Pragma("unroll") for (int k = 0; k < 2; ++k) \
;         acc[ai][bj][m][n] = __builtin_amdgcn_mfma_f32_16x16x32_bf16(Bt[n][k], At[m][k], acc[ai][bj][m][n], 0, 0, 0); __builtin_amdgcn_s_setprio(0); } while (0)
; #define PG8_WAIT_V(n) asm volatile("s_waitcnt vmcnt(" #n ")" ::: "memory")
; #define PG8_WAIT_L(n) asm volatile("s_waitcnt lgkmcnt(" #n ")" ::: "memory")
; #define PG8_BAR __builtin_amdgcn_s_barrier()
; #define PG8_SCHED __builtin_amdgcn_sched_barrier(0)
; template <class Epi, class Sched, bool ALIGN_EPI = false, bool SP2 = false>
; __device__ __forceinline__ void gemm_phase(PG8_LAS unsigned char* lds, const Gemm g, const Sched& S, const Epi& E) {
;     ...
;         for (int t = 0; t < ntc; t += 2) {
;     ...
;             PG8_LDA(At, 1, 1); PG8_STAGE(PG8_SB(1, 0), b3, voffB); PG8_STAGE(PG8_SB(1, 1), b3 + hstep, voffB); PG8_STAGE(PG8_SA(1, 0), a3, voffA);
;             PG8_WAIT_V(8); PG8_WAIT_L(0); PG8_BAR; PG8_MMA(1, 0, At, B0); PG8_MMA(1, 1, At, B1); PG8_BAR; PG8_SCHED;
	s_add_u32 s100, s52, 0xfff00080
	s_addc_u32 s101, s53, -1
	s_add_u32 s98, s50, 0x80
	s_addc_u32 s99, s51, 0
	s_add_i32 s52, s82, s55
	s_mov_b32 m0, s52
	ds_read_b128 v[188:191], v211 offset:49152
	ds_read_b128 v[192:195], v211 offset:50176
	ds_read_b128 v[196:199], v211 offset:51200
	ds_read_b128 v[200:203], v211 offset:52224
	ds_read_b128 v[204:207], v211 offset:53248
	ds_read_b128 v[212:215], v211 offset:54272
	ds_read_b128 v[216:219], v211 offset:55296
	ds_read_b128 v[220:223], v211 offset:56320
	global_load_lds_dwordx4 v134, s[98:99]
	s_add_i32 m0, s52, 0x2000
	s_add_u32 s50, s50, 0x100080
	s_addc_u32 s51, s51, 0
	s_add_i32 s52, s83, s55
	global_load_lds_dwordx4 v136, s[98:99]
	s_mov_b32 m0, s52
	s_nop 0
	global_load_lds_dwordx4 v134, s[50:51]
	s_add_i32 m0, s52, 0x2000
	s_nop 0
	global_load_lds_dwordx4 v136, s[50:51]
	s_mov_b32 m0, s63
	s_nop 0
	global_load_lds_dwordx4 v134, s[100:101]
	s_mov_b32 m0, s64
	s_nop 0
	global_load_lds_dwordx4 v136, s[100:101]
	s_waitcnt vmcnt(8)
	s_waitcnt lgkmcnt(0)
	s_barrier
	s_setprio 1
	s_waitcnt lgkmcnt(0)
	v_mfma_f32_16x16x32_bf16 v[66:69], v[154:157], v[188:191], v[66:69]
	v_mfma_f32_16x16x32_bf16 v[66:69], v[158:161], v[192:195], v[66:69]
	v_mfma_f32_16x16x32_bf16 v[62:65], v[162:165], v[188:191], v[62:65]
	v_mfma_f32_16x16x32_bf16 v[62:65], v[166:169], v[192:195], v[62:65]
	v_mfma_f32_16x16x32_bf16 v[50:53], v[154:157], v[196:199], v[50:53]
	v_mfma_f32_16x16x32_bf16 v[50:53], v[158:161], v[200:203], v[50:53]
	v_mfma_f32_16x16x32_bf16 v[46:49], v[162:165], v[196:199], v[46:49]
	v_mfma_f32_16x16x32_bf16 v[46:49], v[166:169], v[200:203], v[46:49]
	v_mfma_f32_16x16x32_bf16 v[34:37], v[154:157], v[204:207], v[34:37]
	v_mfma_f32_16x16x32_bf16 v[34:37], v[158:161], v[212:215], v[34:37]
	v_mfma_f32_16x16x32_bf16 v[30:33], v[162:165], v[204:207], v[30:33]
	v_mfma_f32_16x16x32_bf16 v[30:33], v[166:169], v[212:215], v[30:33]
	v_mfma_f32_16x16x32_bf16 v[18:21], v[154:157], v[216:219], v[18:21]
	v_mfma_f32_16x16x32_bf16 v[18:21], v[158:161], v[220:223], v[18:21]
	v_mfma_f32_16x16x32_bf16 v[14:17], v[162:165], v[216:219], v[14:17]
	v_mfma_f32_16x16x32_bf16 v[14:17], v[166:169], v[220:223], v[14:17]
	s_setprio 0
	s_setprio 1
	v_mfma_f32_16x16x32_bf16 v[58:61], v[170:173], v[188:191], v[58:61]
	v_mfma_f32_16x16x32_bf16 v[54:57], v[178:181], v[188:191], v[54:57]
	v_mfma_f32_16x16x32_bf16 v[42:45], v[170:173], v[196:199], v[42:45]
	v_mfma_f32_16x16x32_bf16 v[38:41], v[178:181], v[196:199], v[38:41]
	v_mfma_f32_16x16x32_bf16 v[26:29], v[170:173], v[204:207], v[26:29]
	v_mfma_f32_16x16x32_bf16 v[22:25], v[178:181], v[204:207], v[22:25]
	v_mfma_f32_16x16x32_bf16 v[8:11], v[170:173], v[216:219], v[10:13]
	v_mfma_f32_16x16x32_bf16 v[4:7], v[178:181], v[216:219], v[4:7]
	v_mfma_f32_16x16x32_bf16 v[58:61], v[174:177], v[192:195], v[58:61]
	v_mfma_f32_16x16x32_bf16 v[54:57], v[184:187], v[192:195], v[54:57]
	v_mfma_f32_16x16x32_bf16 v[42:45], v[174:177], v[200:203], v[42:45]
	v_mfma_f32_16x16x32_bf16 v[38:41], v[184:187], v[200:203], v[38:41]
	v_mfma_f32_16x16x32_bf16 v[26:29], v[174:177], v[212:215], v[26:29]
	v_mfma_f32_16x16x32_bf16 v[22:25], v[184:187], v[212:215], v[22:25]
	v_mfma_f32_16x16x32_bf16 v[10:13], v[174:177], v[220:223], v[8:11]
	v_mfma_f32_16x16x32_bf16 v[6:9], v[184:187], v[220:223], v[4:7]
	s_setprio 0
	s_barrier
	s_add_u32 s46, s46, 0x100
	s_addc_u32 s47, s47, 0
	s_cmp_ge_i32 s81, s77
	s_cbranch_scc1 .LBB0_2489
	s_mov_b32 s50, s81
	s_branch .LBB0_2485

; #define PG8_STAGE(bufoff, gbase, voff) do { _Pragma("unroll") for (int _i = 0; _i < 2; ++_i) \
;         __builtin_amdgcn_global_load_lds((const unsigned*)((const char*)(gbase) + (voff)[_i]), (PG8_LAS unsigned*)(lds + (bufoff) + ldsw + _i * 8192), 16, 0, 0); } while (0)
; #define PG8_LDA(dst, b, h) do { _Pragma("unroll") for (int m = 0; m < 4; ++m) _Pragma("unroll") for (int k = 0; k < 2; ++k) dst[m][k] = *(const PG8_LAS bf16x8*)(lds + PG8_SA(b, h) + aoff + m * 2048 + k * 1024); } while (0)
; #define PG8_LDB(dst, b, h) do { _Pragma("unroll") for (int n = 0; n < 2; ++n) _Pragma("unroll") for (int k = 0; k < 2; ++k) dst[n][k] = *(const PG8_LAS bf16x8*)(lds + PG8_SB(b, h) + boff + n * 2048 + k * 1024); } while (0)
; #define PG8_MMA(ai, bj, At, Bt) do { __builtin_amdgcn_s_setprio(1); _Pragma("unroll") for (int m = 0; m < 4; ++m) _Pragma("unroll") for (int n = 0; n < 2; ++n) _Pragma("unroll") for (int k = 0; k < 2; ++k) \
;         acc[ai][bj][m][n] = __builtin_amdgcn_mfma_f32_16x16x32_bf16(Bt[n][k], At[m][k], acc[ai][bj][m][n], 0, 0, 0); __builtin_amdgcn_s_setprio(0); } while (0)
; #define PG8_WAIT_V(n) asm volatile("s_waitcnt vmcnt(" #n ")" ::: "memory")
; #define PG8_WAIT_L(n) asm volatile("s_waitcnt lgkmcnt(" #n ")" ::: "memory")
; #define PG8_BAR __builtin_amdgcn_s_barrier()
; #define PG8_SCHED __builtin_amdgcn_sched_barrier(0)
; template <class Epi, class Sched, bool ALIGN_EPI = false, bool SP2 = false>
; __device__ __forceinline__ void gemm_phase(PG8_LAS unsigned char* lds, const Gemm g, const Sched& S, const Epi& E) {
;     ...
;             const char* a2 = last ? nA : cA + (size_t)(t + 2) * kstep; const char* b2 = last ? nB : cB + (size_t)(t + 2) * kstep;
;             const char* a3 = a2 + kstep; const char* b3 = b2 + kstep;
;             if (last && has_next) S.a_ready(nxt);
;             if constexpr (SP2) {
;             PG8_LDB(B0, 0, 0); PG8_LDB(B1, 0, 1); PG8_SCHED; PG8_LDA(At, 0, 0); PG8_STAGE(PG8_SA(1, 1), a1 + hstep, voffA);
;             PG8_WAIT_V(8); PG8_WAIT_L(0); PG8_BAR; PG8_MMA(0, 0, At, B0); PG8_MMA(0, 1, At, B1); PG8_BAR; PG8_SCHED;
;             PG8_LDA(At, 0, 1); PG8_STAGE(PG8_SB(0, 0), b2, voffB); PG8_STAGE(PG8_SB(0, 1), b2 + hstep, voffB); PG8_STAGE(PG8_SA(0, 0), a2, voffA);
;             PG8_WAIT_V(8); PG8_WAIT_L(0); PG8_BAR; PG8_MMA(1, 0, At, B0); PG8_MMA(1, 1, At, B1); PG8_BAR; PG8_SCHED;
.LBB0_2650:
	ds_read_b128 v[10:13], v195
	ds_read_b128 v[14:17], v195 offset:1024
	ds_read_b128 v[42:45], v195 offset:2048
	ds_read_b128 v[46:49], v195 offset:3072
	ds_read_b128 v[50:53], v238
	ds_read_b128 v[54:57], v238 offset:1024
	ds_read_b128 v[58:61], v238 offset:2048
	ds_read_b128 v[62:65], v238 offset:3072
	s_add_u32 s88, s86, 0xfff00080
	s_addc_u32 s89, s87, -1
	s_cmp_eq_u32 s93, 60
	s_cselect_b32 s91, s19, s89
	s_cselect_b32 s90, s69, s88
	s_cselect_b32 s89, s77, s92
	s_cselect_b32 s88, s79, s85
	s_add_i32 m0, s62, 0xc000
	ds_read_b128 v[66:69], v239
	ds_read_b128 v[70:73], v239 offset:1024
	ds_read_b128 v[170:173], v239 offset:2048
	ds_read_b128 v[174:177], v239 offset:3072
	ds_read_b128 v[178:181], v239 offset:4096
	ds_read_b128 v[208:211], v239 offset:5120
	ds_read_b128 v[212:215], v239 offset:6144
	ds_read_b128 v[216:219], v239 offset:7168
	global_load_lds_dwordx4 v200, s[86:87]
	s_add_i32 m0, s62, 0xe000
	s_nop 0
	global_load_lds_dwordx4 v202, s[86:87]
	s_waitcnt vmcnt(8)
	s_waitcnt lgkmcnt(0)
	s_barrier
	s_setprio 1
	s_waitcnt lgkmcnt(0)
	v_mfma_f32_16x16x32_bf16 v[6:9], v[10:13], v[66:69], v[6:9]
	v_mfma_f32_16x16x32_bf16 v[6:9], v[14:17], v[70:73], v[6:9]
	v_mfma_f32_16x16x32_bf16 v[2:5], v[42:45], v[66:69], v[2:5]
	v_mfma_f32_16x16x32_bf16 v[2:5], v[46:49], v[70:73], v[2:5]
	v_mfma_f32_16x16x32_bf16 v[158:161], v[10:13], v[170:173], v[158:161]
	v_mfma_f32_16x16x32_bf16 v[158:161], v[14:17], v[174:177], v[158:161]
	v_mfma_f32_16x16x32_bf16 v[154:157], v[42:45], v[170:173], v[154:157]
	v_mfma_f32_16x16x32_bf16 v[154:157], v[46:49], v[174:177], v[154:157]
	v_mfma_f32_16x16x32_bf16 v[142:145], v[10:13], v[178:181], v[142:145]
	v_mfma_f32_16x16x32_bf16 v[142:145], v[14:17], v[208:211], v[142:145]
	v_mfma_f32_16x16x32_bf16 v[138:141], v[42:45], v[178:181], v[138:141]
	v_mfma_f32_16x16x32_bf16 v[138:141], v[46:49], v[208:211], v[138:141]
	v_mfma_f32_16x16x32_bf16 v[126:129], v[10:13], v[212:215], v[126:129]
	v_mfma_f32_16x16x32_bf16 v[126:129], v[14:17], v[216:219], v[126:129]
	v_mfma_f32_16x16x32_bf16 v[122:125], v[42:45], v[212:215], v[122:125]
	v_mfma_f32_16x16x32_bf16 v[122:125], v[46:49], v[216:219], v[122:125]
	s_setprio 0
	s_setprio 1
	v_mfma_f32_16x16x32_bf16 v[166:169], v[50:53], v[66:69], v[166:169]
	v_mfma_f32_16x16x32_bf16 v[66:69], v[58:61], v[66:69], v[162:165]
	v_mfma_f32_16x16x32_bf16 v[146:149], v[58:61], v[170:173], v[146:149]
	v_mfma_f32_16x16x32_bf16 v[134:137], v[50:53], v[178:181], v[134:137]
	v_mfma_f32_16x16x32_bf16 v[130:133], v[58:61], v[178:181], v[130:133]
	v_mfma_f32_16x16x32_bf16 v[118:121], v[50:53], v[212:215], v[118:121]
	v_mfma_f32_16x16x32_bf16 v[114:117], v[58:61], v[212:215], v[114:117]
	v_mfma_f32_16x16x32_bf16 v[166:169], v[54:57], v[70:73], v[166:169]
	v_mfma_f32_16x16x32_bf16 v[66:69], v[62:65], v[70:73], v[66:69]
	v_mfma_f32_16x16x32_bf16 v[70:73], v[50:53], v[170:173], v[150:153]
	v_mfma_f32_16x16x32_bf16 v[146:149], v[62:65], v[174:177], v[146:149]
	v_mfma_f32_16x16x32_bf16 v[134:137], v[54:57], v[208:211], v[134:137]
	v_mfma_f32_16x16x32_bf16 v[130:133], v[62:65], v[208:211], v[130:133]
	v_mfma_f32_16x16x32_bf16 v[118:121], v[54:57], v[216:219], v[118:121]
	v_mfma_f32_16x16x32_bf16 v[114:117], v[62:65], v[216:219], v[114:117]
	v_mfma_f32_16x16x32_bf16 v[70:73], v[54:57], v[174:177], v[70:73]
	s_setprio 0
	s_barrier
	s_add_i32 vcc_lo, s96, s61
	s_mov_b32 m0, vcc_lo
	ds_read_b128 v[150:153], v239 offset:16384
	ds_read_b128 v[162:165], v239 offset:17408
	ds_read_b128 v[170:173], v239 offset:18432
	ds_read_b128 v[174:177], v239 offset:19456
	ds_read_b128 v[178:181], v239 offset:20480
	ds_read_b128 v[208:211], v239 offset:21504
	ds_read_b128 v[212:215], v239 offset:22528
	ds_read_b128 v[216:219], v239 offset:23552
	global_load_lds_dwordx4 v186, s[88:89]
	s_add_i32 m0, vcc_lo, 0x2000
	s_add_u32 vcc_lo, s88, 0x100000
	s_addc_u32 vcc_hi, s89, 0
	s_add_i32 s58, s70, s61
	global_load_lds_dwordx4 v190, s[88:89]
	s_mov_b32 m0, s58
	s_nop 0
	global_load_lds_dwordx4 v186, vcc
	s_add_i32 m0, s58, 0x2000
	s_nop 0
	global_load_lds_dwordx4 v190, vcc
	s_mov_b32 m0, s62
	s_nop 0
	global_load_lds_dwordx4 v184, s[90:91]
	s_mov_b32 m0, s63
	s_nop 0
	global_load_lds_dwordx4 v188, s[90:91]
	s_waitcnt vmcnt(8)
	s_waitcnt lgkmcnt(0)
	s_barrier
	s_setprio 1
	s_waitcnt lgkmcnt(0)
	v_mfma_f32_16x16x32_bf16 v[110:113], v[10:13], v[150:153], v[110:113]
	v_mfma_f32_16x16x32_bf16 v[106:109], v[42:45], v[150:153], v[106:109]
	v_mfma_f32_16x16x32_bf16 v[94:97], v[10:13], v[170:173], v[94:97]
	v_mfma_f32_16x16x32_bf16 v[90:93], v[42:45], v[170:173], v[90:93]
	v_mfma_f32_16x16x32_bf16 v[78:81], v[10:13], v[178:181], v[78:81]
	v_mfma_f32_16x16x32_bf16 v[74:77], v[42:45], v[178:181], v[74:77]
	v_mfma_f32_16x16x32_bf16 v[10:13], v[10:13], v[212:215], v[30:33]
	v_mfma_f32_16x16x32_bf16 v[110:113], v[14:17], v[162:165], v[110:113]
	v_mfma_f32_16x16x32_bf16 v[106:109], v[46:49], v[162:165], v[106:109]
	v_mfma_f32_16x16x32_bf16 v[94:97], v[14:17], v[174:177], v[94:97]
	v_mfma_f32_16x16x32_bf16 v[90:93], v[46:49], v[174:177], v[90:93]
	v_mfma_f32_16x16x32_bf16 v[78:81], v[14:17], v[208:211], v[78:81]
	v_mfma_f32_16x16x32_bf16 v[74:77], v[46:49], v[208:211], v[74:77]
	v_mfma_f32_16x16x32_bf16 v[10:13], v[14:17], v[216:219], v[10:13]
	v_mfma_f32_16x16x32_bf16 v[14:17], v[42:45], v[212:215], v[26:29]
	v_mfma_f32_16x16x32_bf16 v[14:17], v[46:49], v[216:219], v[14:17]
	s_setprio 0
	s_setprio 1
	v_mfma_f32_16x16x32_bf16 v[26:29], v[50:53], v[150:153], v[102:105]
	v_mfma_f32_16x16x32_bf16 v[42:45], v[54:57], v[162:165], v[26:29]
	v_mfma_f32_16x16x32_bf16 v[26:29], v[58:61], v[150:153], v[98:101]
	v_mfma_f32_16x16x32_bf16 v[46:49], v[62:65], v[162:165], v[26:29]
	v_mfma_f32_16x16x32_bf16 v[26:29], v[50:53], v[170:173], v[86:89]
	v_mfma_f32_16x16x32_bf16 v[86:89], v[54:57], v[174:177], v[26:29]
	v_mfma_f32_16x16x32_bf16 v[26:29], v[58:61], v[170:173], v[82:85]
	v_mfma_f32_16x16x32_bf16 v[82:85], v[62:65], v[174:177], v[26:29]
	v_mfma_f32_16x16x32_bf16 v[26:29], v[50:53], v[178:181], v[38:41]
	v_mfma_f32_16x16x32_bf16 v[38:41], v[54:57], v[208:211], v[26:29]
	v_mfma_f32_16x16x32_bf16 v[26:29], v[58:61], v[178:181], v[34:37]
	v_mfma_f32_16x16x32_bf16 v[22:25], v[50:53], v[212:215], v[22:25]
	v_mfma_f32_16x16x32_bf16 v[18:21], v[58:61], v[212:215], v[18:21]
	v_mfma_f32_16x16x32_bf16 v[34:37], v[62:65], v[208:211], v[26:29]
	v_mfma_f32_16x16x32_bf16 v[22:25], v[54:57], v[216:219], v[22:25]
	v_mfma_f32_16x16x32_bf16 v[18:21], v[62:65], v[216:219], v[18:21]
	s_setprio 0
	s_barrier
; #define PG8_STAGE(bufoff, gbase, voff) do { _Pragma("unroll") for (int _i = 0; _i < 2; ++_i) \
;         __builtin_amdgcn_global_load_lds((const unsigned*)((const char*)(gbase) + (voff)[_i]), (PG8_LAS unsigned*)(lds + (bufoff) + ldsw + _i * 8192), 16, 0, 0); } while (0)
; #define PG8_LDA(dst, b, h) do { _Pragma("unroll") for (int m = 0; m < 4; ++m) _Pragma("unroll") for (int k = 0; k < 2; ++k) dst[m][k] = *(const PG8_LAS bf16x8*)(lds + PG8_SA(b, h) + aoff + m * 2048 + k * 1024); } while (0)
; #define PG8_LDB(dst, b, h) do { _Pragma("unroll") for (int n = 0; n < 2; ++n) _Pragma("unroll") for (int k = 0; k < 2; ++k) dst[n][k] = *(const PG8_LAS bf16x8*)(lds + PG8_SB(b, h) + boff + n * 2048 + k * 1024); } while (0)
; #define PG8_MMA(ai, bj, At, Bt) do { __builtin_amdgcn_s_setprio(1); _Pragma("unroll") for (int m = 0; m < 4; ++m) _Pragma("unroll") for (int n = 0; n < 2; ++n) _Pragma("unroll") for (int k = 0; k < 2; ++k) \
;         acc[ai][bj][m][n] = __builtin_amdgcn_mfma_f32_16x16x32_bf16(Bt[n][k], At[m][k], acc[ai][bj][m][n], 0, 0, 0); __builtin_amdgcn_s_setprio(0); } while (0)
; #define PG8_WAIT_V(n) asm volatile("s_waitcnt vmcnt(" #n ")" ::: "memory")
; #define PG8_WAIT_L(n) asm volatile("s_waitcnt lgkmcnt(" #n ")" ::: "memory")
; #define PG8_BAR __builtin_amdgcn_s_barrier()
; #define PG8_SCHED __builtin_amdgcn_sched_barrier(0)
; template <class Epi, class Sched, bool ALIGN_EPI = false, bool SP2 = false>
; __device__ __forceinline__ void gemm_phase(PG8_LAS unsigned char* lds, const Gemm g, const Sched& S, const Epi& E) {
;     ...
;             PG8_LDB(B0, 1, 0); PG8_LDB(B1, 1, 1); PG8_SCHED; PG8_LDA(At, 1, 0); PG8_STAGE(PG8_SA(0, 1), a2 + hstep, voffA);
;             PG8_WAIT_V(8); PG8_WAIT_L(0); PG8_BAR; PG8_MMA(0, 0, At, B0); PG8_MMA(0, 1, At, B1); PG8_BAR; PG8_SCHED;
;             PG8_LDA(At, 1, 1); PG8_STAGE(PG8_SB(1, 0), b3, voffB); PG8_STAGE(PG8_SB(1, 1), b3 + hstep, voffB); PG8_STAGE(PG8_SA(1, 0), a3, voffA);
;             PG8_WAIT_V(8); PG8_WAIT_L(0); PG8_BAR; PG8_MMA(1, 0, At, B0); PG8_MMA(1, 1, At, B1); PG8_BAR; PG8_SCHED;
	s_add_i32 s58, 0, 0x18000
	s_add_i32 s59, 0, 0x1c000
	v_add_u32_e32 v54, s58, v1
	v_add_u32_e32 v98, s59, v1
	ds_read_b128 v[26:29], v54
	ds_read_b128 v[30:33], v54 offset:1024
	ds_read_b128 v[50:53], v54 offset:2048
	ds_read_b128 v[54:57], v54 offset:3072
	ds_read_b128 v[58:61], v98
	ds_read_b128 v[62:65], v98 offset:1024
	ds_read_b128 v[170:173], v98 offset:2048
	ds_read_b128 v[174:177], v98 offset:3072
	s_add_u32 s90, s90, 0x100000
	s_addc_u32 s91, s91, 0
	s_mov_b32 m0, s73
	ds_read_b128 v[98:101], v239 offset:32768
	ds_read_b128 v[102:105], v239 offset:33792
	ds_read_b128 v[178:181], v239 offset:34816
	ds_read_b128 v[208:211], v239 offset:35840
	ds_read_b128 v[212:215], v239 offset:36864
	ds_read_b128 v[216:219], v239 offset:37888
	ds_read_b128 v[220:223], v239 offset:38912
	ds_read_b128 v[224:227], v239 offset:39936
	global_load_lds_dwordx4 v184, s[90:91]
	s_mov_b32 m0, s75
	s_nop 0
	global_load_lds_dwordx4 v188, s[90:91]
	s_waitcnt vmcnt(8)
	s_waitcnt lgkmcnt(0)
	s_barrier
	s_setprio 1
	s_waitcnt lgkmcnt(0)
	v_mfma_f32_16x16x32_bf16 v[150:153], v[26:29], v[178:181], v[158:161]
	v_mfma_f32_16x16x32_bf16 v[6:9], v[26:29], v[98:101], v[6:9]
	v_mfma_f32_16x16x32_bf16 v[2:5], v[50:53], v[98:101], v[2:5]
	v_mfma_f32_16x16x32_bf16 v[158:161], v[30:33], v[208:211], v[150:153]
	v_mfma_f32_16x16x32_bf16 v[150:153], v[50:53], v[178:181], v[154:157]
	v_mfma_f32_16x16x32_bf16 v[142:145], v[26:29], v[212:215], v[142:145]
	v_mfma_f32_16x16x32_bf16 v[138:141], v[50:53], v[212:215], v[138:141]
	v_mfma_f32_16x16x32_bf16 v[126:129], v[26:29], v[220:223], v[126:129]
	v_mfma_f32_16x16x32_bf16 v[122:125], v[50:53], v[220:223], v[122:125]
	v_mfma_f32_16x16x32_bf16 v[6:9], v[30:33], v[102:105], v[6:9]
	v_mfma_f32_16x16x32_bf16 v[2:5], v[54:57], v[102:105], v[2:5]
	v_mfma_f32_16x16x32_bf16 v[154:157], v[54:57], v[208:211], v[150:153]
	v_mfma_f32_16x16x32_bf16 v[142:145], v[30:33], v[216:219], v[142:145]
	v_mfma_f32_16x16x32_bf16 v[138:141], v[54:57], v[216:219], v[138:141]
	v_mfma_f32_16x16x32_bf16 v[126:129], v[30:33], v[224:227], v[126:129]
	v_mfma_f32_16x16x32_bf16 v[122:125], v[54:57], v[224:227], v[122:125]
	s_setprio 0
	s_setprio 1
	v_mfma_f32_16x16x32_bf16 v[66:69], v[170:173], v[98:101], v[66:69]
	v_mfma_f32_16x16x32_bf16 v[150:153], v[58:61], v[98:101], v[166:169]
	v_mfma_f32_16x16x32_bf16 v[162:165], v[174:177], v[102:105], v[66:69]
	v_mfma_f32_16x16x32_bf16 v[66:69], v[58:61], v[178:181], v[70:73]
	v_mfma_f32_16x16x32_bf16 v[166:169], v[62:65], v[102:105], v[150:153]
	v_mfma_f32_16x16x32_bf16 v[150:153], v[62:65], v[208:211], v[66:69]
	v_mfma_f32_16x16x32_bf16 v[66:69], v[170:173], v[178:181], v[146:149]
	v_mfma_f32_16x16x32_bf16 v[146:149], v[174:177], v[208:211], v[66:69]
	v_mfma_f32_16x16x32_bf16 v[66:69], v[58:61], v[212:215], v[134:137]
	v_mfma_f32_16x16x32_bf16 v[134:137], v[62:65], v[216:219], v[66:69]
	v_mfma_f32_16x16x32_bf16 v[66:69], v[170:173], v[212:215], v[130:133]
	v_mfma_f32_16x16x32_bf16 v[130:133], v[174:177], v[216:219], v[66:69]
	v_mfma_f32_16x16x32_bf16 v[66:69], v[58:61], v[220:223], v[118:121]
	v_mfma_f32_16x16x32_bf16 v[118:121], v[62:65], v[224:227], v[66:69]
	v_mfma_f32_16x16x32_bf16 v[66:69], v[170:173], v[220:223], v[114:117]
	v_mfma_f32_16x16x32_bf16 v[114:117], v[174:177], v[224:227], v[66:69]
	s_setprio 0
	s_barrier
	s_add_i32 s58, s58, s61
	s_add_u32 s100, s88, 0x80
	s_addc_u32 s101, s89, 0
	s_mov_b32 m0, s58
	s_nop 1
	ds_read_b128 v[66:69], v239 offset:49152
	ds_read_b128 v[70:73], v239 offset:50176
	ds_read_b128 v[178:181], v239 offset:51200
	ds_read_b128 v[208:211], v239 offset:52224
	ds_read_b128 v[212:215], v239 offset:53248
	ds_read_b128 v[216:219], v239 offset:54272
	ds_read_b128 v[220:223], v239 offset:55296
	ds_read_b128 v[224:227], v239 offset:56320
	global_load_lds_dwordx4 v186, s[100:101]
	s_add_i32 m0, s58, 0x2000
	s_add_i32 s58, s59, s61
	global_load_lds_dwordx4 v190, s[100:101]
	s_add_u32 s88, s88, 0x100080
	s_addc_u32 s89, s89, 0
	s_add_u32 s100, s90, 0xfff00080
	s_addc_u32 s101, s91, -1
	s_mov_b32 m0, s58
	s_nop 0
	global_load_lds_dwordx4 v186, s[88:89]
	s_add_i32 m0, s58, 0x2000
	s_nop 0
	global_load_lds_dwordx4 v190, s[88:89]
	s_mov_b32 m0, s29
	s_nop 0
	global_load_lds_dwordx4 v184, s[100:101]
	s_mov_b32 m0, s95
	s_nop 0
	global_load_lds_dwordx4 v188, s[100:101]
	s_waitcnt vmcnt(8)
	s_waitcnt lgkmcnt(0)
	s_barrier
	s_setprio 1
	s_waitcnt lgkmcnt(0)
	v_mfma_f32_16x16x32_bf16 v[98:101], v[26:29], v[66:69], v[110:113]
	v_mfma_f32_16x16x32_bf16 v[94:97], v[26:29], v[178:181], v[94:97]
	v_mfma_f32_16x16x32_bf16 v[78:81], v[26:29], v[212:215], v[78:81]
	v_mfma_f32_16x16x32_bf16 v[10:13], v[26:29], v[220:223], v[10:13]
	v_mfma_f32_16x16x32_bf16 v[110:113], v[30:33], v[70:73], v[98:101]
	v_mfma_f32_16x16x32_bf16 v[98:101], v[50:53], v[66:69], v[106:109]
	v_mfma_f32_16x16x32_bf16 v[94:97], v[30:33], v[208:211], v[94:97]
	v_mfma_f32_16x16x32_bf16 v[90:93], v[50:53], v[178:181], v[90:93]
	v_mfma_f32_16x16x32_bf16 v[78:81], v[30:33], v[216:219], v[78:81]
	v_mfma_f32_16x16x32_bf16 v[74:77], v[50:53], v[212:215], v[74:77]
	v_mfma_f32_16x16x32_bf16 v[30:33], v[30:33], v[224:227], v[10:13]
	v_mfma_f32_16x16x32_bf16 v[10:13], v[50:53], v[220:223], v[14:17]
	v_mfma_f32_16x16x32_bf16 v[106:109], v[54:57], v[70:73], v[98:101]
	v_mfma_f32_16x16x32_bf16 v[90:93], v[54:57], v[208:211], v[90:93]
	v_mfma_f32_16x16x32_bf16 v[74:77], v[54:57], v[216:219], v[74:77]
	v_mfma_f32_16x16x32_bf16 v[26:29], v[54:57], v[224:227], v[10:13]
	s_setprio 0
	s_setprio 1
	v_mfma_f32_16x16x32_bf16 v[10:13], v[58:61], v[66:69], v[42:45]
	v_mfma_f32_16x16x32_bf16 v[102:105], v[62:65], v[70:73], v[10:13]
	v_mfma_f32_16x16x32_bf16 v[10:13], v[170:173], v[66:69], v[46:49]
	v_mfma_f32_16x16x32_bf16 v[98:101], v[174:177], v[70:73], v[10:13]
	v_mfma_f32_16x16x32_bf16 v[10:13], v[58:61], v[178:181], v[86:89]
	v_mfma_f32_16x16x32_bf16 v[86:89], v[62:65], v[208:211], v[10:13]
	v_mfma_f32_16x16x32_bf16 v[10:13], v[170:173], v[178:181], v[82:85]
	v_mfma_f32_16x16x32_bf16 v[82:85], v[174:177], v[208:211], v[10:13]
	v_mfma_f32_16x16x32_bf16 v[10:13], v[58:61], v[212:215], v[38:41]
	v_mfma_f32_16x16x32_bf16 v[38:41], v[62:65], v[216:219], v[10:13]
	v_mfma_f32_16x16x32_bf16 v[10:13], v[170:173], v[212:215], v[34:37]
	v_mfma_f32_16x16x32_bf16 v[34:37], v[174:177], v[216:219], v[10:13]
	v_mfma_f32_16x16x32_bf16 v[10:13], v[58:61], v[220:223], v[22:25]
	v_mfma_f32_16x16x32_bf16 v[22:25], v[62:65], v[224:227], v[10:13]
	v_mfma_f32_16x16x32_bf16 v[10:13], v[170:173], v[220:223], v[18:21]
	v_mfma_f32_16x16x32_bf16 v[18:21], v[174:177], v[224:227], v[10:13]
	s_setprio 0
	s_barrier
	s_add_i32 s93, s93, 2
	s_add_u32 s86, s86, 0x100
	s_addc_u32 s87, s87, 0
	s_add_u32 s85, s85, 0x100
	s_addc_u32 s92, s92, 0
	s_cmp_gt_u32 s93, 61
	s_cbranch_scc0 .LBB0_2650
	s_and_b64 vcc, exec, s[42:43]
	s_cbranch_vccz .LBB0_2653
	s_barrier

; #define PG8_STAGE(bufoff, gbase, voff) do { _Pragma("unroll") for (int _i = 0; _i < 2; ++_i) \
;         __builtin_amdgcn_global_load_lds((const unsigned*)((const char*)(gbase) + (voff)[_i]), (PG8_LAS unsigned*)(lds + (bufoff) + ldsw + _i * 8192), 16, 0, 0); } while (0)
; #define PG8_LDA(dst, b, h) do { _Pragma("unroll") for (int m = 0; m < 4; ++m) _Pragma("unroll") for (int k = 0; k < 2; ++k) dst[m][k] = *(const PG8_LAS bf16x8*)(lds + PG8_SA(b, h) + aoff + m * 2048 + k * 1024); } while (0)
; #define PG8_LDB(dst, b, h) do { _Pragma("unroll") for (int n = 0; n < 2; ++n) _Pragma("unroll") for (int k = 0; k < 2; ++k) dst[n][k] = *(const PG8_LAS bf16x8*)(lds + PG8_SB(b, h) + boff + n * 2048 + k * 1024); } while (0)
; #define PG8_MMA(ai, bj, At, Bt) do { __builtin_amdgcn_s_setprio(1); _Pragma("unroll") for (int m = 0; m < 4; ++m) _Pragma("unroll") for (int n = 0; n < 2; ++n) _Pragma("unroll") for (int k = 0; k < 2; ++k) \
;         acc[ai][bj][m][n] = __builtin_amdgcn_mfma_f32_16x16x32_bf16(Bt[n][k], At[m][k], acc[ai][bj][m][n], 0, 0, 0); __builtin_amdgcn_s_setprio(0); } while (0)
; #define PG8_WAIT_V(n) asm volatile("s_waitcnt vmcnt(" #n ")" ::: "memory")
; #define PG8_WAIT_L(n) asm volatile("s_waitcnt lgkmcnt(" #n ")" ::: "memory")
; #define PG8_BAR __builtin_amdgcn_s_barrier()
; #define PG8_SCHED __builtin_amdgcn_sched_barrier(0)
; template <class Epi, class Sched, bool ALIGN_EPI = false, bool SP2 = false>
; __device__ __forceinline__ void gemm_phase(PG8_LAS unsigned char* lds, const Gemm g, const Sched& S, const Epi& E) {
;     ...
;             const char* a2 = last ? nA : cA + (size_t)(t + 2) * kstep; const char* b2 = last ? nB : cB + (size_t)(t + 2) * kstep;
;             const char* a3 = a2 + kstep; const char* b3 = b2 + kstep;
;             if (last && has_next) S.a_ready(nxt);
;             if constexpr (SP2) {
;             PG8_LDB(B0, 0, 0); PG8_LDB(B1, 0, 1); PG8_SCHED; PG8_LDA(At, 0, 0); PG8_STAGE(PG8_SA(1, 1), a1 + hstep, voffA);
;             PG8_WAIT_V(8); PG8_WAIT_L(0); PG8_BAR; PG8_MMA(0, 0, At, B0); PG8_MMA(0, 1, At, B1); PG8_BAR; PG8_SCHED;
;             PG8_LDA(At, 0, 1); PG8_STAGE(PG8_SB(0, 0), b2, voffB); PG8_STAGE(PG8_SB(0, 1), b2 + hstep, voffB); PG8_STAGE(PG8_SA(0, 0), a2, voffA);
;             PG8_WAIT_V(8); PG8_WAIT_L(0); PG8_BAR; PG8_MMA(1, 0, At, B0); PG8_MMA(1, 1, At, B1); PG8_BAR; PG8_SCHED;
.LBB0_3522:
	ds_read_b128 v[144:147], v177
	ds_read_b128 v[148:151], v177 offset:1024
	ds_read_b128 v[152:155], v177 offset:2048
	ds_read_b128 v[156:159], v177 offset:3072
	ds_read_b128 v[160:163], v178
	ds_read_b128 v[164:167], v178 offset:1024
	ds_read_b128 v[168:171], v178 offset:2048
	ds_read_b128 v[172:175], v178 offset:3072
	s_add_u32 s40, s38, 0x100
	s_addc_u32 s41, s39, 0
	s_cmp_eq_u32 s69, s71
	s_cselect_b32 s45, s35, s41
	s_cselect_b32 s44, s34, s40
	s_cselect_b32 s43, s37, s70
	s_cselect_b32 s42, s36, s31
	s_add_i32 m0, s51, 0xc000
	ds_read_b128 v[180:183], v179
	ds_read_b128 v[184:187], v179 offset:1024
	ds_read_b128 v[188:191], v179 offset:2048
	ds_read_b128 v[192:195], v179 offset:3072
	ds_read_b128 v[196:199], v179 offset:4096
	ds_read_b128 v[200:203], v179 offset:5120
	ds_read_b128 v[204:207], v179 offset:6144
	ds_read_b128 v[208:211], v179 offset:7168
	global_load_lds_dwordx4 v138, s[38:39]
	s_add_i32 m0, s51, 0xe000
	s_nop 0
	global_load_lds_dwordx4 v140, s[38:39]
	s_waitcnt vmcnt(8)
	s_waitcnt lgkmcnt(0)
	s_barrier
	s_setprio 1
	s_waitcnt lgkmcnt(0)
	v_mfma_f32_16x16x32_bf16 v[126:129], v[144:147], v[180:183], v[126:129]
	v_mfma_f32_16x16x32_bf16 v[126:129], v[148:151], v[184:187], v[126:129]
	v_mfma_f32_16x16x32_bf16 v[122:125], v[152:155], v[180:183], v[122:125]
	v_mfma_f32_16x16x32_bf16 v[122:125], v[156:159], v[184:187], v[122:125]
	v_mfma_f32_16x16x32_bf16 v[110:113], v[144:147], v[188:191], v[110:113]
	v_mfma_f32_16x16x32_bf16 v[110:113], v[148:151], v[192:195], v[110:113]
	v_mfma_f32_16x16x32_bf16 v[106:109], v[152:155], v[188:191], v[106:109]
	v_mfma_f32_16x16x32_bf16 v[106:109], v[156:159], v[192:195], v[106:109]
	v_mfma_f32_16x16x32_bf16 v[94:97], v[144:147], v[196:199], v[94:97]
	v_mfma_f32_16x16x32_bf16 v[94:97], v[148:151], v[200:203], v[94:97]
	v_mfma_f32_16x16x32_bf16 v[90:93], v[152:155], v[196:199], v[90:93]
	v_mfma_f32_16x16x32_bf16 v[90:93], v[156:159], v[200:203], v[90:93]
	v_mfma_f32_16x16x32_bf16 v[78:81], v[144:147], v[204:207], v[78:81]
	v_mfma_f32_16x16x32_bf16 v[78:81], v[148:151], v[208:211], v[78:81]
	v_mfma_f32_16x16x32_bf16 v[74:77], v[152:155], v[204:207], v[74:77]
	v_mfma_f32_16x16x32_bf16 v[74:77], v[156:159], v[208:211], v[74:77]
	s_setprio 0
	s_setprio 1
	v_mfma_f32_16x16x32_bf16 v[118:121], v[160:163], v[180:183], v[118:121]
	v_mfma_f32_16x16x32_bf16 v[118:121], v[164:167], v[184:187], v[118:121]
	v_mfma_f32_16x16x32_bf16 v[114:117], v[168:171], v[180:183], v[114:117]
	v_mfma_f32_16x16x32_bf16 v[114:117], v[172:175], v[184:187], v[114:117]
	v_mfma_f32_16x16x32_bf16 v[102:105], v[160:163], v[188:191], v[102:105]
	v_mfma_f32_16x16x32_bf16 v[102:105], v[164:167], v[192:195], v[102:105]
	v_mfma_f32_16x16x32_bf16 v[98:101], v[168:171], v[188:191], v[98:101]
	v_mfma_f32_16x16x32_bf16 v[98:101], v[172:175], v[192:195], v[98:101]
	v_mfma_f32_16x16x32_bf16 v[86:89], v[160:163], v[196:199], v[86:89]
	v_mfma_f32_16x16x32_bf16 v[86:89], v[164:167], v[200:203], v[86:89]
	v_mfma_f32_16x16x32_bf16 v[82:85], v[168:171], v[196:199], v[82:85]
	v_mfma_f32_16x16x32_bf16 v[82:85], v[172:175], v[200:203], v[82:85]
	v_mfma_f32_16x16x32_bf16 v[70:73], v[160:163], v[204:207], v[70:73]
	v_mfma_f32_16x16x32_bf16 v[70:73], v[164:167], v[208:211], v[70:73]
	v_mfma_f32_16x16x32_bf16 v[66:69], v[168:171], v[204:207], v[66:69]
	v_mfma_f32_16x16x32_bf16 v[66:69], v[172:175], v[208:211], v[66:69]
	s_setprio 0
	s_barrier
	s_add_i32 s38, s63, s50
	s_mov_b32 m0, s38
	ds_read_b128 v[180:183], v179 offset:16384
	ds_read_b128 v[184:187], v179 offset:17408
	ds_read_b128 v[188:191], v179 offset:18432
	ds_read_b128 v[192:195], v179 offset:19456
	ds_read_b128 v[196:199], v179 offset:20480
	ds_read_b128 v[200:203], v179 offset:21504
	ds_read_b128 v[204:207], v179 offset:22528
	ds_read_b128 v[208:211], v179 offset:23552
	global_load_lds_dwordx4 v130, s[42:43]
	s_add_i32 m0, s38, 0x2000
	s_add_u32 s38, s42, 0x300000
	s_addc_u32 s39, s43, 0
	s_add_i32 s58, s64, s50
	global_load_lds_dwordx4 v132, s[42:43]
	s_mov_b32 m0, s58
	s_nop 0
	global_load_lds_dwordx4 v130, s[38:39]
	s_add_i32 m0, s58, 0x2000
	s_nop 0
	global_load_lds_dwordx4 v132, s[38:39]
	s_mov_b32 m0, s51
	s_nop 0
	global_load_lds_dwordx4 v130, s[44:45]
	s_mov_b32 m0, s52
	s_nop 0
	global_load_lds_dwordx4 v132, s[44:45]
	s_waitcnt vmcnt(8)
	s_waitcnt lgkmcnt(0)
	s_barrier
	s_setprio 1
	s_waitcnt lgkmcnt(0)
	v_mfma_f32_16x16x32_bf16 v[62:65], v[144:147], v[180:183], v[62:65]
	v_mfma_f32_16x16x32_bf16 v[62:65], v[148:151], v[184:187], v[62:65]
	v_mfma_f32_16x16x32_bf16 v[58:61], v[152:155], v[180:183], v[58:61]
	v_mfma_f32_16x16x32_bf16 v[58:61], v[156:159], v[184:187], v[58:61]
	v_mfma_f32_16x16x32_bf16 v[46:49], v[144:147], v[188:191], v[46:49]
	v_mfma_f32_16x16x32_bf16 v[46:49], v[148:151], v[192:195], v[46:49]
	v_mfma_f32_16x16x32_bf16 v[42:45], v[152:155], v[188:191], v[42:45]
	v_mfma_f32_16x16x32_bf16 v[42:45], v[156:159], v[192:195], v[42:45]
	v_mfma_f32_16x16x32_bf16 v[30:33], v[144:147], v[196:199], v[30:33]
	v_mfma_f32_16x16x32_bf16 v[30:33], v[148:151], v[200:203], v[30:33]
	v_mfma_f32_16x16x32_bf16 v[26:29], v[152:155], v[196:199], v[26:29]
	v_mfma_f32_16x16x32_bf16 v[26:29], v[156:159], v[200:203], v[26:29]
	v_mfma_f32_16x16x32_bf16 v[14:17], v[144:147], v[204:207], v[14:17]
	v_mfma_f32_16x16x32_bf16 v[14:17], v[148:151], v[208:211], v[14:17]
	v_mfma_f32_16x16x32_bf16 v[10:13], v[152:155], v[204:207], v[10:13]
	v_mfma_f32_16x16x32_bf16 v[10:13], v[156:159], v[208:211], v[10:13]
	s_setprio 0
	s_setprio 1
	v_mfma_f32_16x16x32_bf16 v[54:57], v[160:163], v[180:183], v[54:57]
	v_mfma_f32_16x16x32_bf16 v[54:57], v[164:167], v[184:187], v[54:57]
	v_mfma_f32_16x16x32_bf16 v[50:53], v[168:171], v[180:183], v[50:53]
	v_mfma_f32_16x16x32_bf16 v[50:53], v[172:175], v[184:187], v[50:53]
	v_mfma_f32_16x16x32_bf16 v[38:41], v[160:163], v[188:191], v[38:41]
	v_mfma_f32_16x16x32_bf16 v[38:41], v[164:167], v[192:195], v[38:41]
	v_mfma_f32_16x16x32_bf16 v[34:37], v[168:171], v[188:191], v[34:37]
	v_mfma_f32_16x16x32_bf16 v[34:37], v[172:175], v[192:195], v[34:37]
	v_mfma_f32_16x16x32_bf16 v[22:25], v[160:163], v[196:199], v[22:25]
	v_mfma_f32_16x16x32_bf16 v[22:25], v[164:167], v[200:203], v[22:25]
	v_mfma_f32_16x16x32_bf16 v[18:21], v[168:171], v[196:199], v[18:21]
	v_mfma_f32_16x16x32_bf16 v[18:21], v[172:175], v[200:203], v[18:21]
	v_mfma_f32_16x16x32_bf16 v[6:9], v[160:163], v[204:207], v[6:9]
	v_mfma_f32_16x16x32_bf16 v[6:9], v[164:167], v[208:211], v[6:9]
	v_mfma_f32_16x16x32_bf16 v[2:5], v[168:171], v[204:207], v[2:5]
	v_mfma_f32_16x16x32_bf16 v[2:5], v[172:175], v[208:211], v[2:5]
	s_setprio 0
	s_barrier
; #define PG8_STAGE(bufoff, gbase, voff) do { _Pragma("unroll") for (int _i = 0; _i < 2; ++_i) \
;         __builtin_amdgcn_global_load_lds((const unsigned*)((const char*)(gbase) + (voff)[_i]), (PG8_LAS unsigned*)(lds + (bufoff) + ldsw + _i * 8192), 16, 0, 0); } while (0)
; #define PG8_LDA(dst, b, h) do { _Pragma("unroll") for (int m = 0; m < 4; ++m) _Pragma("unroll") for (int k = 0; k < 2; ++k) dst[m][k] = *(const PG8_LAS bf16x8*)(lds + PG8_SA(b, h) + aoff + m * 2048 + k * 1024); } while (0)
; #define PG8_LDB(dst, b, h) do { _Pragma("unroll") for (int n = 0; n < 2; ++n) _Pragma("unroll") for (int k = 0; k < 2; ++k) dst[n][k] = *(const PG8_LAS bf16x8*)(lds + PG8_SB(b, h) + boff + n * 2048 + k * 1024); } while (0)
; #define PG8_MMA(ai, bj, At, Bt) do { __builtin_amdgcn_s_setprio(1); _Pragma("unroll") for (int m = 0; m < 4; ++m) _Pragma("unroll") for (int n = 0; n < 2; ++n) _Pragma("unroll") for (int k = 0; k < 2; ++k) \
;         acc[ai][bj][m][n] = __builtin_amdgcn_mfma_f32_16x16x32_bf16(Bt[n][k], At[m][k], acc[ai][bj][m][n], 0, 0, 0); __builtin_amdgcn_s_setprio(0); } while (0)
; #define PG8_WAIT_V(n) asm volatile("s_waitcnt vmcnt(" #n ")" ::: "memory")
; #define PG8_WAIT_L(n) asm volatile("s_waitcnt lgkmcnt(" #n ")" ::: "memory")
; #define PG8_BAR __builtin_amdgcn_s_barrier()
; #define PG8_SCHED __builtin_amdgcn_sched_barrier(0)
;     __device__ __forceinline__ void operator()(const f32x4 (&acc)[2][2][4][2], const Unit& u, int wr, int wc, int fr, int fq) const {
;     ...
;         if (u.ntu != 192) {
; template <class Epi, class Sched, bool ALIGN_EPI = false, bool SP2 = false>
; __device__ __forceinline__ void gemm_phase(PG8_LAS unsigned char* lds, const Gemm g, const Sched& S, const Epi& E) {
;     ...
;             PG8_LDB(B0, 1, 0); PG8_LDB(B1, 1, 1); PG8_SCHED; PG8_LDA(At, 1, 0); PG8_STAGE(PG8_SA(0, 1), a2 + hstep, voffA);
;             PG8_WAIT_V(8); PG8_WAIT_L(0); PG8_BAR; PG8_MMA(0, 0, At, B0); PG8_MMA(0, 1, At, B1); PG8_BAR; PG8_SCHED;
;             PG8_LDA(At, 1, 1); PG8_STAGE(PG8_SB(1, 0), b3, voffB); PG8_STAGE(PG8_SB(1, 1), b3 + hstep, voffB); PG8_STAGE(PG8_SA(1, 0), a3, voffA);
;             PG8_WAIT_V(8); PG8_WAIT_L(0); PG8_BAR; PG8_MMA(1, 0, At, B0); PG8_MMA(1, 1, At, B1); PG8_BAR; PG8_SCHED;
	s_add_i32 s58, 0, 0x18000
	v_add_u32_e32 v134, s58, v1
	s_add_i32 s59, 0, 0x1c000
	ds_read_b128 v[144:147], v134
	ds_read_b128 v[148:151], v134 offset:1024
	ds_read_b128 v[152:155], v134 offset:2048
	ds_read_b128 v[156:159], v134 offset:3072
	v_add_u32_e32 v134, s59, v1
	ds_read_b128 v[160:163], v134
	ds_read_b128 v[164:167], v134 offset:1024
	ds_read_b128 v[168:171], v134 offset:2048
	ds_read_b128 v[172:175], v134 offset:3072
	s_add_u32 s38, s44, 0x300000
	s_addc_u32 s39, s45, 0
	s_mov_b32 m0, s53
	ds_read_b128 v[180:183], v179 offset:32768
	ds_read_b128 v[184:187], v179 offset:33792
	ds_read_b128 v[188:191], v179 offset:34816
	ds_read_b128 v[192:195], v179 offset:35840
	ds_read_b128 v[196:199], v179 offset:36864
	ds_read_b128 v[200:203], v179 offset:37888
	ds_read_b128 v[204:207], v179 offset:38912
	ds_read_b128 v[208:211], v179 offset:39936
	global_load_lds_dwordx4 v130, s[38:39]
	s_mov_b32 m0, s54
	s_nop 0
	global_load_lds_dwordx4 v132, s[38:39]
	s_waitcnt vmcnt(8)
	s_waitcnt lgkmcnt(0)
	s_barrier
	s_setprio 1
	s_waitcnt lgkmcnt(0)
	v_mfma_f32_16x16x32_bf16 v[126:129], v[144:147], v[180:183], v[126:129]
	v_mfma_f32_16x16x32_bf16 v[126:129], v[148:151], v[184:187], v[126:129]
	v_mfma_f32_16x16x32_bf16 v[122:125], v[152:155], v[180:183], v[122:125]
	v_mfma_f32_16x16x32_bf16 v[122:125], v[156:159], v[184:187], v[122:125]
	v_mfma_f32_16x16x32_bf16 v[110:113], v[144:147], v[188:191], v[110:113]
	v_mfma_f32_16x16x32_bf16 v[110:113], v[148:151], v[192:195], v[110:113]
	v_mfma_f32_16x16x32_bf16 v[106:109], v[152:155], v[188:191], v[106:109]
	v_mfma_f32_16x16x32_bf16 v[106:109], v[156:159], v[192:195], v[106:109]
	v_mfma_f32_16x16x32_bf16 v[94:97], v[144:147], v[196:199], v[94:97]
	v_mfma_f32_16x16x32_bf16 v[94:97], v[148:151], v[200:203], v[94:97]
	v_mfma_f32_16x16x32_bf16 v[90:93], v[152:155], v[196:199], v[90:93]
	v_mfma_f32_16x16x32_bf16 v[90:93], v[156:159], v[200:203], v[90:93]
	v_mfma_f32_16x16x32_bf16 v[78:81], v[144:147], v[204:207], v[78:81]
	v_mfma_f32_16x16x32_bf16 v[78:81], v[148:151], v[208:211], v[78:81]
	v_mfma_f32_16x16x32_bf16 v[74:77], v[152:155], v[204:207], v[74:77]
	v_mfma_f32_16x16x32_bf16 v[74:77], v[156:159], v[208:211], v[74:77]
	s_setprio 0
	s_setprio 1
	v_mfma_f32_16x16x32_bf16 v[118:121], v[160:163], v[180:183], v[118:121]
	v_mfma_f32_16x16x32_bf16 v[118:121], v[164:167], v[184:187], v[118:121]
	v_mfma_f32_16x16x32_bf16 v[114:117], v[168:171], v[180:183], v[114:117]
	v_mfma_f32_16x16x32_bf16 v[114:117], v[172:175], v[184:187], v[114:117]
	v_mfma_f32_16x16x32_bf16 v[102:105], v[160:163], v[188:191], v[102:105]
	v_mfma_f32_16x16x32_bf16 v[102:105], v[164:167], v[192:195], v[102:105]
	v_mfma_f32_16x16x32_bf16 v[98:101], v[168:171], v[188:191], v[98:101]
	v_mfma_f32_16x16x32_bf16 v[98:101], v[172:175], v[192:195], v[98:101]
	v_mfma_f32_16x16x32_bf16 v[86:89], v[160:163], v[196:199], v[86:89]
	v_mfma_f32_16x16x32_bf16 v[86:89], v[164:167], v[200:203], v[86:89]
	v_mfma_f32_16x16x32_bf16 v[82:85], v[168:171], v[196:199], v[82:85]
	v_mfma_f32_16x16x32_bf16 v[82:85], v[172:175], v[200:203], v[82:85]
	v_mfma_f32_16x16x32_bf16 v[70:73], v[160:163], v[204:207], v[70:73]
	v_mfma_f32_16x16x32_bf16 v[70:73], v[164:167], v[208:211], v[70:73]
	v_mfma_f32_16x16x32_bf16 v[66:69], v[168:171], v[204:207], v[66:69]
	v_mfma_f32_16x16x32_bf16 v[66:69], v[172:175], v[208:211], v[66:69]
	s_setprio 0
	s_barrier
	s_add_i32 s38, s58, s50
	s_add_u32 s98, s42, 0x80
	s_addc_u32 s99, s43, 0
	s_add_u32 s100, s44, 0x80
	s_addc_u32 s101, s45, 0
	s_mov_b32 m0, s38
	ds_read_b128 v[180:183], v179 offset:49152
	ds_read_b128 v[184:187], v179 offset:50176
	ds_read_b128 v[188:191], v179 offset:51200
	ds_read_b128 v[192:195], v179 offset:52224
	ds_read_b128 v[196:199], v179 offset:53248
	ds_read_b128 v[200:203], v179 offset:54272
	ds_read_b128 v[204:207], v179 offset:55296
	ds_read_b128 v[208:211], v179 offset:56320
	global_load_lds_dwordx4 v130, s[98:99]
	s_add_i32 m0, s38, 0x2000
	s_add_u32 s38, s42, 0x300080
	s_addc_u32 s39, s43, 0
	s_add_i32 s42, s59, s50
	global_load_lds_dwordx4 v132, s[98:99]
	s_mov_b32 m0, s42
	s_nop 0
	global_load_lds_dwordx4 v130, s[38:39]
	s_add_i32 m0, s42, 0x2000
	s_nop 0
	global_load_lds_dwordx4 v132, s[38:39]
	s_mov_b32 m0, s57
	s_nop 0
	global_load_lds_dwordx4 v130, s[100:101]
	s_mov_b32 m0, s60
	s_nop 0
	global_load_lds_dwordx4 v132, s[100:101]
	s_waitcnt vmcnt(8)
	s_waitcnt lgkmcnt(0)
	s_barrier
	s_setprio 1
	s_waitcnt lgkmcnt(0)
	v_mfma_f32_16x16x32_bf16 v[62:65], v[144:147], v[180:183], v[62:65]
	v_mfma_f32_16x16x32_bf16 v[62:65], v[148:151], v[184:187], v[62:65]
	v_mfma_f32_16x16x32_bf16 v[58:61], v[152:155], v[180:183], v[58:61]
	v_mfma_f32_16x16x32_bf16 v[58:61], v[156:159], v[184:187], v[58:61]
	v_mfma_f32_16x16x32_bf16 v[46:49], v[144:147], v[188:191], v[46:49]
	v_mfma_f32_16x16x32_bf16 v[46:49], v[148:151], v[192:195], v[46:49]
	v_mfma_f32_16x16x32_bf16 v[42:45], v[152:155], v[188:191], v[42:45]
	v_mfma_f32_16x16x32_bf16 v[42:45], v[156:159], v[192:195], v[42:45]
	v_mfma_f32_16x16x32_bf16 v[30:33], v[144:147], v[196:199], v[30:33]
	v_mfma_f32_16x16x32_bf16 v[30:33], v[148:151], v[200:203], v[30:33]
	v_mfma_f32_16x16x32_bf16 v[26:29], v[152:155], v[196:199], v[26:29]
	v_mfma_f32_16x16x32_bf16 v[26:29], v[156:159], v[200:203], v[26:29]
	v_mfma_f32_16x16x32_bf16 v[14:17], v[144:147], v[204:207], v[14:17]
	v_mfma_f32_16x16x32_bf16 v[14:17], v[148:151], v[208:211], v[14:17]
	v_mfma_f32_16x16x32_bf16 v[10:13], v[152:155], v[204:207], v[10:13]
	v_mfma_f32_16x16x32_bf16 v[10:13], v[156:159], v[208:211], v[10:13]
	s_setprio 0
	s_setprio 1
	v_mfma_f32_16x16x32_bf16 v[54:57], v[160:163], v[180:183], v[54:57]
	v_mfma_f32_16x16x32_bf16 v[54:57], v[164:167], v[184:187], v[54:57]
	v_mfma_f32_16x16x32_bf16 v[50:53], v[168:171], v[180:183], v[50:53]
	v_mfma_f32_16x16x32_bf16 v[50:53], v[172:175], v[184:187], v[50:53]
	v_mfma_f32_16x16x32_bf16 v[38:41], v[160:163], v[188:191], v[38:41]
	v_mfma_f32_16x16x32_bf16 v[38:41], v[164:167], v[192:195], v[38:41]
	v_mfma_f32_16x16x32_bf16 v[34:37], v[168:171], v[188:191], v[34:37]
	v_mfma_f32_16x16x32_bf16 v[34:37], v[172:175], v[192:195], v[34:37]
	v_mfma_f32_16x16x32_bf16 v[22:25], v[160:163], v[196:199], v[22:25]
	v_mfma_f32_16x16x32_bf16 v[22:25], v[164:167], v[200:203], v[22:25]
	v_mfma_f32_16x16x32_bf16 v[18:21], v[168:171], v[196:199], v[18:21]
	v_mfma_f32_16x16x32_bf16 v[18:21], v[172:175], v[200:203], v[18:21]
	v_mfma_f32_16x16x32_bf16 v[6:9], v[160:163], v[204:207], v[6:9]
	v_mfma_f32_16x16x32_bf16 v[6:9], v[164:167], v[208:211], v[6:9]
	v_mfma_f32_16x16x32_bf16 v[2:5], v[168:171], v[204:207], v[2:5]
	v_mfma_f32_16x16x32_bf16 v[2:5], v[172:175], v[208:211], v[2:5]
	s_setprio 0
	s_barrier
	s_add_i32 s42, s71, 2
	s_add_u32 s31, s31, 0x100
	s_addc_u32 s70, s70, 0
	s_cmp_ge_i32 s71, s69
	s_mov_b64 s[38:39], s[40:41]
	s_mov_b32 s71, s42
	s_cbranch_scc0 .LBB0_3522
	s_and_b64 vcc, exec, s[20:21]
	s_cbranch_vccz .LBB0_3543
	s_barrier
	v_lshl_or_b32 v144, s5, 8, v176
	s_cmpk_eq_i32 s69, 0xc0
	s_mov_b64 s[38:39], -1
	s_cbranch_scc0 .LBB0_3544
